# FFN-in GEMM epilogue: dead zero-inits before full-row DPP rotates removed; conv3 taps as one f32 FMA chain (was copy,copy,pk_mul,fma,add,add)
# speedup vs baseline: 1.0156x; 1.0149x over previous
.LBB0_869:
	v_lshl_or_b32 v180, s1, 7, v202
	v_ashrrev_i32_e32 v181, 31, v180
	v_lshlrev_b64 v[190:191], 2, v[180:181]
	v_lshl_add_u64 v[68:69], s[46:47], 0, v[190:191]
	v_lshl_add_u64 v[70:71], s[44:45], 0, v[190:191]
	v_lshl_add_u64 v[72:73], s[50:51], 0, v[190:191]
	v_lshl_add_u64 v[84:85], s[48:49], 0, v[190:191]
	global_load_dwordx4 v[64:67], v[68:69], off
	global_load_dwordx4 v[80:83], v[68:69], off offset:16
	global_load_dwordx4 v[92:95], v[70:71], off offset:16
	global_load_dwordx4 v[76:79], v[70:71], off
	global_load_dwordx4 v[88:91], v[72:73], off offset:16
	s_nop 0
	global_load_dwordx4 v[72:75], v[72:73], off
	s_nop 0
	global_load_dwordx4 v[68:71], v[84:85], off
	s_nop 0
	global_load_dwordx4 v[84:87], v[84:85], off offset:16
	s_lshl_b32 s1, s0, 2
	s_add_i32 s62, s1, s71
	s_ashr_i32 s63, s62, 31
	v_mov_b32_dpp v183, v148 row_ror:1 row_mask:0xf bank_mask:0xf
	v_mov_b32_dpp v209, v148 row_ror:2 row_mask:0xf bank_mask:0xf
	v_mov_b32_dpp v185, v149 row_ror:1 row_mask:0xf bank_mask:0xf
	v_mov_b32_dpp v210, v149 row_ror:2 row_mask:0xf bank_mask:0xf
	v_mov_b32_dpp v187, v150 row_ror:1 row_mask:0xf bank_mask:0xf
	v_mov_b32_dpp v211, v150 row_ror:2 row_mask:0xf bank_mask:0xf
	v_mov_b32_dpp v189, v151 row_ror:1 row_mask:0xf bank_mask:0xf
	v_mov_b32_dpp v212, v151 row_ror:2 row_mask:0xf bank_mask:0xf
	v_mov_b32_dpp v193, v144 row_ror:1 row_mask:0xf bank_mask:0xf
	v_mov_b32_dpp v213, v144 row_ror:2 row_mask:0xf bank_mask:0xf
	v_mov_b32_dpp v195, v145 row_ror:1 row_mask:0xf bank_mask:0xf
	v_mov_b32_dpp v192, v145 row_ror:2 row_mask:0xf bank_mask:0xf
	v_mov_b32_dpp v197, v146 row_ror:1 row_mask:0xf bank_mask:0xf
	v_mov_b32_dpp v194, v146 row_ror:2 row_mask:0xf bank_mask:0xf
	v_mov_b32_dpp v199, v147 row_ror:1 row_mask:0xf bank_mask:0xf
	v_mov_b32_dpp v196, v147 row_ror:2 row_mask:0xf bank_mask:0xf
	s_lshl_b64 s[64:65], s[62:63], 1
	v_mov_b32_dpp v183, v148 row_shr:1 row_mask:0xf bank_mask:0xf
	v_mov_b32_dpp v209, v148 row_shr:2 row_mask:0xf bank_mask:0xf
	v_mov_b32_dpp v185, v149 row_shr:1 row_mask:0xf bank_mask:0xf
	v_mov_b32_dpp v210, v149 row_shr:2 row_mask:0xf bank_mask:0xf
	v_mov_b32_dpp v187, v150 row_shr:1 row_mask:0xf bank_mask:0xf
	v_mov_b32_dpp v211, v150 row_shr:2 row_mask:0xf bank_mask:0xf
	v_mov_b32_dpp v189, v151 row_shr:1 row_mask:0xf bank_mask:0xf
	v_mov_b32_dpp v212, v151 row_shr:2 row_mask:0xf bank_mask:0xf
	v_mov_b32_dpp v193, v144 row_shr:1 row_mask:0xf bank_mask:0xf
	v_mov_b32_dpp v213, v144 row_shr:2 row_mask:0xf bank_mask:0xf
	v_mov_b32_dpp v195, v145 row_shr:1 row_mask:0xf bank_mask:0xf
	v_mov_b32_dpp v192, v145 row_shr:2 row_mask:0xf bank_mask:0xf
	v_mov_b32_dpp v197, v146 row_shr:1 row_mask:0xf bank_mask:0xf
	v_mov_b32_dpp v194, v146 row_shr:2 row_mask:0xf bank_mask:0xf
	v_mov_b32_dpp v199, v147 row_shr:1 row_mask:0xf bank_mask:0xf
	v_mov_b32_dpp v196, v147 row_shr:2 row_mask:0xf bank_mask:0xf
	s_and_saveexec_b64 s[66:67], s[2:3]
	s_xor_b64 s[66:67], exec, s[66:67]
	s_cbranch_execz .LBB0_871
	v_or_b32_e32 v186, s64, v168
	v_mov_b64_e32 v[182:183], s[14:15]
	v_mov_b64_e32 v[184:185], s[18:19]
	v_mad_u64_u32 v[182:183], s[86:87], v186, s84, v[182:183]
	v_mad_u64_u32 v[184:185], s[86:87], v186, s84, v[184:185]
	v_mad_i32_i24 v183, s65, v207, v183
	v_mad_i32_i24 v185, s65, v207, v185
	v_lshl_add_u64 v[182:183], v[182:183], 0, v[190:191]
	v_lshl_add_u64 v[184:185], v[184:185], 0, v[190:191]
	global_store_dwordx4 v[182:183], v[148:151], off
	global_store_dwordx4 v[182:183], v[144:147], off offset:16
	global_store_dwordx4 v[184:185], v[152:155], off
	global_store_dwordx4 v[184:185], v[156:159], off offset:16
	s_waitcnt vmcnt(0)
	v_mov_b32_e32 v188, v91
	v_mov_b32_e32 v186, v89
	v_mov_b32_e32 v184, v75
	v_mov_b32_e32 v182, v73
.LBB0_871:
	s_or_saveexec_b64 s[66:67], s[66:67]
	v_lshl_add_u32 v208, s0, 8, v169
	s_xor_b64 exec, exec, s[66:67]
	s_cbranch_execz .LBB0_873
	v_mov_b32_e32 v214, v147
	s_waitcnt vmcnt(0)
	v_mov_b32_e32 v215, v95
	v_mov_b32_e32 v198, v91
	v_pk_mul_f32 v[198:199], v[214:215], v[198:199]
	s_nop 0
	v_fma_f32 v182, v83, v196, v199
	v_add_f32_e32 v182, v198, v182
	v_add_f32_e32 v182, v87, v182
	v_mov_b32_e32 v198, v146
	v_mov_b32_e32 v199, v94
	v_mov_b32_e32 v196, v90
	v_mul_f32_e32 v184, v182, v182
	v_pk_mul_f32 v[196:197], v[198:199], v[196:197]
	v_fmamk_f32 v184, v184, 0xbdd2d3e8, v206
	v_fma_f32 v186, v82, v194, v197
	v_mul_f32_e32 v184, v182, v184
	v_add_f32_e32 v186, v196, v186
	v_exp_f32_e32 v184, v184
	v_add_f32_e32 v186, v86, v186
	v_mul_f32_e32 v188, v186, v186
	v_fmamk_f32 v188, v188, 0xbdd2d3e8, v206
	v_mul_f32_e32 v188, v186, v188
	v_exp_f32_e32 v188, v188
	v_add_f32_e32 v184, 1.0, v184
	v_rcp_f32_e32 v184, v184
	v_mov_b32_e32 v196, v145
	v_add_f32_e32 v188, 1.0, v188
	v_mov_b32_e32 v197, v93
	v_mov_b32_e32 v194, v89
	v_rcp_f32_e32 v188, v188
	v_mul_f32_e32 v182, v182, v184
	v_pk_mul_f32 v[194:195], v[196:197], v[194:195]
	v_mul_f32_e32 v198, v159, v182
	v_fma_f32 v182, v81, v192, v195
	v_add_f32_e32 v182, v194, v182
	v_mov_b32_e32 v194, v144
	v_mov_b32_e32 v195, v92
	v_mov_b32_e32 v192, v88
	v_pk_mul_f32 v[192:193], v[194:195], v[192:193]
	v_mul_f32_e32 v159, v186, v188
	v_fma_f32 v186, v80, v213, v193
	v_add_f32_e32 v182, v85, v182
	v_add_f32_e32 v186, v192, v186
	v_mul_f32_e32 v184, v182, v182
	v_add_f32_e32 v186, v84, v186
	v_fmamk_f32 v184, v184, 0xbdd2d3e8, v206
	v_mul_f32_e32 v188, v186, v186
	v_mul_f32_e32 v184, v182, v184
	v_fmamk_f32 v188, v188, 0xbdd2d3e8, v206
	v_exp_f32_e32 v184, v184
	v_mul_f32_e32 v188, v186, v188
	v_exp_f32_e32 v188, v188
	v_mul_f32_e32 v192, v158, v159
	v_add_f32_e32 v158, 1.0, v184
	v_rcp_f32_e32 v184, v158
	v_add_f32_e32 v158, 1.0, v188
	v_rcp_f32_e32 v193, v158
	v_fma_f32 v158, v75, v151, v71
	v_fmac_f32_e32 v158, v79, v189
	s_nop 0
	v_fma_f32 v188, v67, v212, v158
	v_mul_f32_e32 v158, v188, v188
	v_fmamk_f32 v158, v158, 0xbdd2d3e8, v206
	v_mul_f32_e32 v158, v188, v158
	v_exp_f32_e32 v158, v158
	v_mul_f32_e32 v159, v182, v184
	v_mul_f32_e32 v189, v157, v159
	v_mul_f32_e32 v157, v186, v193
	v_add_f32_e32 v158, 1.0, v158
	v_rcp_f32_e32 v182, v158
	v_fma_f32 v158, v74, v150, v70
	v_fmac_f32_e32 v158, v78, v187
	v_mul_f32_e32 v186, v156, v157
	v_fma_f32 v158, v66, v211, v158
	v_mul_f32_e32 v159, v158, v158
	v_fmamk_f32 v159, v159, 0xbdd2d3e8, v206
	v_mul_f32_e32 v159, v158, v159
	v_exp_f32_e32 v159, v159
	v_mul_f32_e32 v156, v188, v182
	v_mul_f32_e32 v155, v155, v156
	v_add_f32_e32 v156, 1.0, v159
	v_rcp_f32_e32 v159, v156
	v_fma_f32 v156, v73, v149, v69
	v_fmac_f32_e32 v156, v77, v185
	v_fma_f32 v184, v65, v210, v156
	v_mul_f32_e32 v156, v184, v184
	v_fmamk_f32 v156, v156, 0xbdd2d3e8, v206
	v_mul_f32_e32 v156, v184, v156
	v_exp_f32_e32 v185, v156
	v_fma_f32 v156, v72, v148, v68
	v_fmac_f32_e32 v156, v76, v183
	v_mul_f32_e32 v158, v158, v159
	v_fma_f32 v156, v64, v209, v156
	v_mul_f32_e32 v157, v156, v156
	v_fmamk_f32 v157, v157, 0xbdd2d3e8, v206
	v_mul_f32_e32 v157, v156, v157
	v_exp_f32_e32 v157, v157
	v_add_f32_e32 v159, 1.0, v185
	v_rcp_f32_e32 v159, v159
	v_mul_f32_e32 v154, v154, v158
	v_add_f32_e32 v157, 1.0, v157
	v_rcp_f32_e32 v157, v157
	v_mul_f32_e32 v158, v184, v159
	v_mul_f32_e32 v153, v153, v158
	v_mov_b32_e32 v182, v73
	v_mul_f32_e32 v156, v156, v157
	v_mul_f32_e32 v152, v152, v156
	v_mov_b64_e32 v[156:157], s[10:11]
	v_mad_i64_i32 v[156:157], s[0:1], v208, s85, v[156:157]
	v_cvt_pk_bf16_f32 v152, v152, v153
	v_cvt_pk_bf16_f32 v153, v154, v155
	v_cvt_pk_bf16_f32 v154, v186, v189
	v_lshl_add_u64 v[156:157], v[180:181], 1, v[156:157]
	v_mov_b32_e32 v184, v75
	v_mov_b32_e32 v186, v89
	v_mov_b32_e32 v188, v91
	v_cvt_pk_bf16_f32 v155, v192, v198
	global_store_dwordx4 v[156:157], v[152:155], off
.LBB0_873:
	s_or_b64 exec, exec, s[66:67]
	s_waitcnt vmcnt(0)
	v_mov_b32_dpp v73, v148 row_ror:1 row_mask:0xf bank_mask:0xf
	v_mov_b32_dpp v152, v148 row_ror:2 row_mask:0xf bank_mask:0xf
	v_mov_b32_dpp v183, v149 row_ror:1 row_mask:0xf bank_mask:0xf
	v_mov_b32_dpp v148, v149 row_ror:2 row_mask:0xf bank_mask:0xf
	v_mov_b32_dpp v75, v150 row_ror:1 row_mask:0xf bank_mask:0xf
	v_mov_b32_dpp v149, v150 row_ror:2 row_mask:0xf bank_mask:0xf
	v_mov_b32_dpp v185, v151 row_ror:1 row_mask:0xf bank_mask:0xf
	v_mov_b32_dpp v150, v151 row_ror:2 row_mask:0xf bank_mask:0xf
	v_mov_b32_dpp v91, v146 row_ror:1 row_mask:0xf bank_mask:0xf
	v_mov_b32_dpp v154, v146 row_ror:2 row_mask:0xf bank_mask:0xf
	v_mov_b32_dpp v189, v147 row_ror:1 row_mask:0xf bank_mask:0xf
	v_mov_b32_dpp v89, v144 row_ror:1 row_mask:0xf bank_mask:0xf
	v_mov_b32_dpp v151, v144 row_ror:2 row_mask:0xf bank_mask:0xf
	v_mov_b32_dpp v187, v145 row_ror:1 row_mask:0xf bank_mask:0xf
	v_mov_b32_dpp v153, v145 row_ror:2 row_mask:0xf bank_mask:0xf
	v_mov_b32_dpp v189, v131 row_shr:1 row_mask:0xf bank_mask:0xf
	v_mov_b32_dpp v146, v147 row_ror:2 row_mask:0xf bank_mask:0xf
	v_mov_b32_dpp v146, v131 row_shr:2 row_mask:0xf bank_mask:0xf
	v_fma_f32 v144, v188, v131, v87
	v_fmac_f32_e32 v144, v95, v189
	v_mov_b32_dpp v91, v130 row_shr:1 row_mask:0xf bank_mask:0xf
	v_fma_f32 v146, v83, v146, v144
	v_mul_f32_e32 v144, v146, v146
	v_fmamk_f32 v144, v144, 0xbdd2d3e8, v206
	v_mul_f32_e32 v144, v146, v144
	v_exp_f32_e32 v147, v144
	v_mov_b32_dpp v154, v130 row_shr:2 row_mask:0xf bank_mask:0xf
	v_fma_f32 v144, v90, v130, v86
	v_fmac_f32_e32 v144, v94, v91
	v_mov_b32_dpp v187, v129 row_shr:1 row_mask:0xf bank_mask:0xf
	v_fma_f32 v91, v82, v154, v144
	v_mul_f32_e32 v144, v91, v91
	v_fmamk_f32 v144, v144, 0xbdd2d3e8, v206
	v_mul_f32_e32 v144, v91, v144
	v_exp_f32_e32 v144, v144
	v_add_f32_e32 v145, 1.0, v147
	v_rcp_f32_e32 v145, v145
	v_mov_b32_dpp v153, v129 row_shr:2 row_mask:0xf bank_mask:0xf
	v_add_f32_e32 v144, 1.0, v144
	v_rcp_f32_e32 v144, v144
	v_mul_f32_e32 v145, v146, v145
	v_mul_f32_e32 v146, v143, v145
	v_mul_f32_e32 v91, v91, v144
	v_fma_f32 v144, v186, v129, v85
	v_fmac_f32_e32 v144, v93, v187
	v_mov_b32_dpp v89, v128 row_shr:1 row_mask:0xf bank_mask:0xf
	v_fma_f32 v153, v81, v153, v144
	v_mov_b32_dpp v151, v128 row_shr:2 row_mask:0xf bank_mask:0xf
	v_fma_f32 v144, v88, v128, v84
	v_fmac_f32_e32 v144, v92, v89
	v_fma_f32 v89, v80, v151, v144
	v_mul_f32_e32 v143, v153, v153
	v_fmamk_f32 v143, v143, 0xbdd2d3e8, v206
	v_mul_f32_e32 v144, v89, v89
	v_mul_f32_e32 v143, v153, v143
	v_fmamk_f32 v144, v144, 0xbdd2d3e8, v206
	v_exp_f32_e32 v143, v143
	v_mul_f32_e32 v144, v89, v144
	v_exp_f32_e32 v144, v144
	v_mul_f32_e32 v91, v142, v91
	v_add_f32_e32 v142, 1.0, v143
	v_rcp_f32_e32 v145, v142
	v_add_f32_e32 v142, 1.0, v144
	v_mov_b32_dpp v185, v135 row_shr:1 row_mask:0xf bank_mask:0xf
	v_rcp_f32_e32 v144, v142
	v_mov_b32_dpp v150, v135 row_shr:2 row_mask:0xf bank_mask:0xf
	v_fma_f32 v142, v184, v135, v71
	v_fmac_f32_e32 v142, v79, v185
	v_mov_b32_dpp v75, v134 row_shr:1 row_mask:0xf bank_mask:0xf
	v_fma_f32 v150, v67, v150, v142
	v_mul_f32_e32 v142, v150, v150
	v_fmamk_f32 v142, v142, 0xbdd2d3e8, v206
	v_mul_f32_e32 v142, v150, v142
	v_exp_f32_e32 v142, v142
	v_mul_f32_e32 v143, v153, v145
	v_mul_f32_e32 v145, v141, v143
	v_add_f32_e32 v141, 1.0, v142
	v_mov_b32_dpp v149, v134 row_shr:2 row_mask:0xf bank_mask:0xf
	v_fma_f32 v142, v74, v134, v70
	v_fmac_f32_e32 v142, v78, v75
	v_rcp_f32_e32 v141, v141
	v_fma_f32 v75, v66, v149, v142
	v_mul_f32_e32 v142, v75, v75
	v_fmamk_f32 v142, v142, 0xbdd2d3e8, v206
	v_mul_f32_e32 v142, v75, v142
	v_exp_f32_e32 v142, v142
	v_mul_f32_e32 v89, v89, v144
	v_mul_f32_e32 v89, v140, v89
	v_mul_f32_e32 v140, v150, v141
	v_mul_f32_e32 v139, v139, v140
	v_add_f32_e32 v140, 1.0, v142
	v_mov_b32_dpp v183, v133 row_shr:1 row_mask:0xf bank_mask:0xf
	v_rcp_f32_e32 v142, v140
	v_mov_b32_dpp v148, v133 row_shr:2 row_mask:0xf bank_mask:0xf
	v_fma_f32 v140, v182, v133, v69
	v_fmac_f32_e32 v140, v77, v183
	v_mov_b32_dpp v73, v132 row_shr:1 row_mask:0xf bank_mask:0xf
	v_fma_f32 v143, v65, v148, v140
	v_mul_f32_e32 v140, v143, v143
	v_fmamk_f32 v140, v140, 0xbdd2d3e8, v206
	v_mul_f32_e32 v140, v143, v140
	v_exp_f32_e32 v144, v140
	v_mov_b32_dpp v152, v132 row_shr:2 row_mask:0xf bank_mask:0xf
	v_fma_f32 v140, v72, v132, v68
	v_fmac_f32_e32 v140, v76, v73
	v_mul_f32_e32 v75, v75, v142
	v_fma_f32 v73, v64, v152, v140
	v_mul_f32_e32 v140, v73, v73
	v_fmamk_f32 v140, v140, 0xbdd2d3e8, v206
	v_mul_f32_e32 v140, v73, v140
	v_exp_f32_e32 v140, v140
	v_add_f32_e32 v141, 1.0, v144
	v_rcp_f32_e32 v141, v141
	v_mul_f32_e32 v75, v138, v75
	v_add_f32_e32 v140, 1.0, v140
	v_rcp_f32_e32 v140, v140
	v_mul_f32_e32 v138, v143, v141
	v_or_b32_e32 v147, 16, v208
	v_mul_f32_e32 v137, v137, v138
	v_mul_f32_e32 v73, v73, v140
	v_mul_f32_e32 v73, v136, v73
	v_cvt_pk_bf16_f32 v140, v73, v137
	v_cvt_pk_bf16_f32 v141, v75, v139
	v_mov_b64_e32 v[138:139], s[10:11]
	v_cvt_pk_bf16_f32 v142, v89, v145
	v_mad_i64_i32 v[144:145], s[0:1], v147, s85, v[138:139]
	v_lshlrev_b64 v[136:137], 1, v[180:181]
	v_lshl_add_u64 v[144:145], v[144:145], 0, v[136:137]
	v_cvt_pk_bf16_f32 v143, v91, v146
	global_store_dwordx4 v[144:145], v[140:143], off
	v_mov_b32_dpp v73, v132 row_ror:1 row_mask:0xf bank_mask:0xf
	v_mov_b32_dpp v183, v133 row_ror:1 row_mask:0xf bank_mask:0xf
	v_mov_b32_dpp v140, v132 row_ror:2 row_mask:0xf bank_mask:0xf
	v_mov_b32_dpp v132, v133 row_ror:2 row_mask:0xf bank_mask:0xf
	v_mov_b32_dpp v75, v134 row_ror:1 row_mask:0xf bank_mask:0xf
	v_mov_b32_dpp v133, v134 row_ror:2 row_mask:0xf bank_mask:0xf
	v_mov_b32_dpp v185, v135 row_ror:1 row_mask:0xf bank_mask:0xf
	v_mov_b32_dpp v134, v135 row_ror:2 row_mask:0xf bank_mask:0xf
	v_mov_b32_dpp v91, v130 row_ror:1 row_mask:0xf bank_mask:0xf
	v_mov_b32_dpp v142, v130 row_ror:2 row_mask:0xf bank_mask:0xf
	v_mov_b32_dpp v189, v131 row_ror:1 row_mask:0xf bank_mask:0xf
	v_mov_b32_dpp v89, v128 row_ror:1 row_mask:0xf bank_mask:0xf
	v_mov_b32_dpp v135, v128 row_ror:2 row_mask:0xf bank_mask:0xf
	v_mov_b32_dpp v187, v129 row_ror:1 row_mask:0xf bank_mask:0xf
	v_mov_b32_dpp v141, v129 row_ror:2 row_mask:0xf bank_mask:0xf
	v_mov_b32_dpp v189, v115 row_shr:1 row_mask:0xf bank_mask:0xf
	v_mov_b32_dpp v130, v131 row_ror:2 row_mask:0xf bank_mask:0xf
	v_mov_b32_dpp v130, v115 row_shr:2 row_mask:0xf bank_mask:0xf
	v_fma_f32 v128, v188, v115, v87
	v_fmac_f32_e32 v128, v95, v189
	v_mov_b32_dpp v91, v114 row_shr:1 row_mask:0xf bank_mask:0xf
	v_fma_f32 v130, v83, v130, v128
	v_mul_f32_e32 v128, v130, v130
	v_fmamk_f32 v128, v128, 0xbdd2d3e8, v206
	v_mul_f32_e32 v128, v130, v128
	v_exp_f32_e32 v131, v128
	v_mov_b32_dpp v142, v114 row_shr:2 row_mask:0xf bank_mask:0xf
	v_fma_f32 v128, v90, v114, v86
	v_fmac_f32_e32 v128, v94, v91
	v_mov_b32_dpp v187, v113 row_shr:1 row_mask:0xf bank_mask:0xf
	v_fma_f32 v91, v82, v142, v128
	v_mul_f32_e32 v128, v91, v91
	v_fmamk_f32 v128, v128, 0xbdd2d3e8, v206
	v_mul_f32_e32 v128, v91, v128
	v_exp_f32_e32 v128, v128
	v_add_f32_e32 v129, 1.0, v131
	v_rcp_f32_e32 v129, v129
	v_mov_b32_dpp v141, v113 row_shr:2 row_mask:0xf bank_mask:0xf
	v_add_f32_e32 v128, 1.0, v128
	v_rcp_f32_e32 v128, v128
	v_mul_f32_e32 v129, v130, v129
	v_mul_f32_e32 v130, v127, v129
	v_mul_f32_e32 v91, v91, v128
	v_fma_f32 v128, v186, v113, v85
	v_fmac_f32_e32 v128, v93, v187
	v_mov_b32_dpp v89, v112 row_shr:1 row_mask:0xf bank_mask:0xf
	v_fma_f32 v141, v81, v141, v128
	v_mov_b32_dpp v135, v112 row_shr:2 row_mask:0xf bank_mask:0xf
	v_fma_f32 v128, v88, v112, v84
	v_fmac_f32_e32 v128, v92, v89
	v_fma_f32 v89, v80, v135, v128
	v_mul_f32_e32 v127, v141, v141
	v_fmamk_f32 v127, v127, 0xbdd2d3e8, v206
	v_mul_f32_e32 v128, v89, v89
	v_mul_f32_e32 v127, v141, v127
	v_fmamk_f32 v128, v128, 0xbdd2d3e8, v206
	v_exp_f32_e32 v127, v127
	v_mul_f32_e32 v128, v89, v128
	v_exp_f32_e32 v128, v128
	v_mul_f32_e32 v91, v126, v91
	v_add_f32_e32 v126, 1.0, v127
	v_rcp_f32_e32 v129, v126
	v_add_f32_e32 v126, 1.0, v128
	v_mov_b32_dpp v185, v119 row_shr:1 row_mask:0xf bank_mask:0xf
	v_rcp_f32_e32 v128, v126
	v_mov_b32_dpp v134, v119 row_shr:2 row_mask:0xf bank_mask:0xf
	v_fma_f32 v126, v184, v119, v71
	v_fmac_f32_e32 v126, v79, v185
	v_mov_b32_dpp v75, v118 row_shr:1 row_mask:0xf bank_mask:0xf
	v_fma_f32 v134, v67, v134, v126
	v_mul_f32_e32 v126, v134, v134
	v_fmamk_f32 v126, v126, 0xbdd2d3e8, v206
	v_mul_f32_e32 v126, v134, v126
	v_exp_f32_e32 v126, v126
	v_mul_f32_e32 v127, v141, v129
	v_mul_f32_e32 v129, v125, v127
	v_add_f32_e32 v125, 1.0, v126
	v_mov_b32_dpp v133, v118 row_shr:2 row_mask:0xf bank_mask:0xf
	v_fma_f32 v126, v74, v118, v70
	v_fmac_f32_e32 v126, v78, v75
	v_rcp_f32_e32 v125, v125
	v_fma_f32 v75, v66, v133, v126
	v_mul_f32_e32 v126, v75, v75
	v_fmamk_f32 v126, v126, 0xbdd2d3e8, v206
	v_mul_f32_e32 v126, v75, v126
	v_exp_f32_e32 v126, v126
	v_mul_f32_e32 v89, v89, v128
	v_mul_f32_e32 v89, v124, v89
	v_mul_f32_e32 v124, v134, v125
	v_mul_f32_e32 v123, v123, v124
	v_add_f32_e32 v124, 1.0, v126
	v_mov_b32_dpp v183, v117 row_shr:1 row_mask:0xf bank_mask:0xf
	v_rcp_f32_e32 v126, v124
	v_mov_b32_dpp v132, v117 row_shr:2 row_mask:0xf bank_mask:0xf
	v_fma_f32 v124, v182, v117, v69
	v_fmac_f32_e32 v124, v77, v183
	v_mov_b32_dpp v73, v116 row_shr:1 row_mask:0xf bank_mask:0xf
	v_fma_f32 v127, v65, v132, v124
	v_mul_f32_e32 v124, v127, v127
	v_fmamk_f32 v124, v124, 0xbdd2d3e8, v206
	v_mul_f32_e32 v124, v127, v124
	v_exp_f32_e32 v128, v124
	v_mov_b32_dpp v140, v116 row_shr:2 row_mask:0xf bank_mask:0xf
	v_fma_f32 v124, v72, v116, v68
	v_fmac_f32_e32 v124, v76, v73
	v_or_b32_e32 v131, 32, v208
	v_fma_f32 v73, v64, v140, v124
	v_mul_f32_e32 v124, v73, v73
	v_fmamk_f32 v124, v124, 0xbdd2d3e8, v206
	v_mul_f32_e32 v124, v73, v124
	v_exp_f32_e32 v124, v124
	v_add_f32_e32 v125, 1.0, v128
	v_rcp_f32_e32 v125, v125
	v_mul_f32_e32 v75, v75, v126
	v_add_f32_e32 v124, 1.0, v124
	v_rcp_f32_e32 v124, v124
	v_mul_f32_e32 v75, v122, v75
	v_mul_f32_e32 v122, v127, v125
	v_mul_f32_e32 v121, v121, v122
	v_mul_f32_e32 v73, v73, v124
	v_mad_i64_i32 v[124:125], s[0:1], v131, s85, v[138:139]
	v_mul_f32_e32 v73, v120, v73
	v_cvt_pk_bf16_f32 v120, v73, v121
	v_lshl_add_u64 v[124:125], v[124:125], 0, v[136:137]
	v_cvt_pk_bf16_f32 v121, v75, v123
	v_cvt_pk_bf16_f32 v122, v89, v129
	v_cvt_pk_bf16_f32 v123, v91, v130
	global_store_dwordx4 v[124:125], v[120:123], off
	v_mov_b32_dpp v73, v116 row_ror:1 row_mask:0xf bank_mask:0xf
	v_mov_b32_dpp v183, v117 row_ror:1 row_mask:0xf bank_mask:0xf
	v_mov_b32_dpp v120, v116 row_ror:2 row_mask:0xf bank_mask:0xf
	v_mov_b32_dpp v116, v117 row_ror:2 row_mask:0xf bank_mask:0xf
	v_mov_b32_dpp v75, v118 row_ror:1 row_mask:0xf bank_mask:0xf
	v_mov_b32_dpp v117, v118 row_ror:2 row_mask:0xf bank_mask:0xf
	v_mov_b32_dpp v185, v119 row_ror:1 row_mask:0xf bank_mask:0xf
	v_mov_b32_dpp v118, v119 row_ror:2 row_mask:0xf bank_mask:0xf
	v_mov_b32_dpp v91, v114 row_ror:1 row_mask:0xf bank_mask:0xf
	v_mov_b32_dpp v122, v114 row_ror:2 row_mask:0xf bank_mask:0xf
	v_mov_b32_dpp v189, v115 row_ror:1 row_mask:0xf bank_mask:0xf
	v_mov_b32_dpp v89, v112 row_ror:1 row_mask:0xf bank_mask:0xf
	v_mov_b32_dpp v119, v112 row_ror:2 row_mask:0xf bank_mask:0xf
	v_mov_b32_dpp v187, v113 row_ror:1 row_mask:0xf bank_mask:0xf
	v_mov_b32_dpp v121, v113 row_ror:2 row_mask:0xf bank_mask:0xf
	v_mov_b32_dpp v189, v103 row_shr:1 row_mask:0xf bank_mask:0xf
	v_mov_b32_dpp v114, v115 row_ror:2 row_mask:0xf bank_mask:0xf
	v_mov_b32_dpp v114, v103 row_shr:2 row_mask:0xf bank_mask:0xf
	v_fma_f32 v112, v188, v103, v87
	v_fmac_f32_e32 v112, v95, v189
	v_mov_b32_dpp v91, v102 row_shr:1 row_mask:0xf bank_mask:0xf
	v_fma_f32 v114, v83, v114, v112
	v_mul_f32_e32 v112, v114, v114
	v_fmamk_f32 v112, v112, 0xbdd2d3e8, v206
	v_mul_f32_e32 v112, v114, v112
	v_exp_f32_e32 v115, v112
	v_mov_b32_dpp v122, v102 row_shr:2 row_mask:0xf bank_mask:0xf
	v_fma_f32 v112, v90, v102, v86
	v_fmac_f32_e32 v112, v94, v91
	v_mov_b32_dpp v187, v101 row_shr:1 row_mask:0xf bank_mask:0xf
	v_fma_f32 v91, v82, v122, v112
	v_mul_f32_e32 v112, v91, v91
	v_fmamk_f32 v112, v112, 0xbdd2d3e8, v206
	v_mul_f32_e32 v112, v91, v112
	v_exp_f32_e32 v112, v112
	v_add_f32_e32 v113, 1.0, v115
	v_rcp_f32_e32 v113, v113
	v_mov_b32_dpp v121, v101 row_shr:2 row_mask:0xf bank_mask:0xf
	v_add_f32_e32 v112, 1.0, v112
	v_rcp_f32_e32 v112, v112
	v_mul_f32_e32 v113, v114, v113
	v_mul_f32_e32 v114, v111, v113
	v_mul_f32_e32 v91, v91, v112
	v_fma_f32 v112, v186, v101, v85
	v_fmac_f32_e32 v112, v93, v187
	v_mov_b32_dpp v89, v100 row_shr:1 row_mask:0xf bank_mask:0xf
	v_fma_f32 v121, v81, v121, v112
	v_mov_b32_dpp v119, v100 row_shr:2 row_mask:0xf bank_mask:0xf
	v_fma_f32 v112, v88, v100, v84
	v_fmac_f32_e32 v112, v92, v89
	v_fma_f32 v89, v80, v119, v112
	v_mul_f32_e32 v111, v121, v121
	v_fmamk_f32 v111, v111, 0xbdd2d3e8, v206
	v_mul_f32_e32 v112, v89, v89
	v_mul_f32_e32 v111, v121, v111
	v_fmamk_f32 v112, v112, 0xbdd2d3e8, v206
	v_exp_f32_e32 v111, v111
	v_mul_f32_e32 v112, v89, v112
	v_exp_f32_e32 v112, v112
	v_mul_f32_e32 v91, v110, v91
	v_add_f32_e32 v110, 1.0, v111
	v_rcp_f32_e32 v113, v110
	v_add_f32_e32 v110, 1.0, v112
	v_mov_b32_dpp v185, v107 row_shr:1 row_mask:0xf bank_mask:0xf
	v_rcp_f32_e32 v112, v110
	v_mov_b32_dpp v118, v107 row_shr:2 row_mask:0xf bank_mask:0xf
	v_fma_f32 v110, v184, v107, v71
	v_fmac_f32_e32 v110, v79, v185
	v_mov_b32_dpp v75, v106 row_shr:1 row_mask:0xf bank_mask:0xf
	v_fma_f32 v118, v67, v118, v110
	v_mul_f32_e32 v110, v118, v118
	v_fmamk_f32 v110, v110, 0xbdd2d3e8, v206
	v_mul_f32_e32 v110, v118, v110
	v_exp_f32_e32 v110, v110
	v_mul_f32_e32 v111, v121, v113
	v_mul_f32_e32 v113, v109, v111
	v_add_f32_e32 v109, 1.0, v110
	v_mov_b32_dpp v117, v106 row_shr:2 row_mask:0xf bank_mask:0xf
	v_fma_f32 v110, v74, v106, v70
	v_fmac_f32_e32 v110, v78, v75
	v_rcp_f32_e32 v109, v109
	v_fma_f32 v75, v66, v117, v110
	v_mul_f32_e32 v110, v75, v75
	v_fmamk_f32 v110, v110, 0xbdd2d3e8, v206
	v_mul_f32_e32 v110, v75, v110
	v_exp_f32_e32 v110, v110
	v_mul_f32_e32 v89, v89, v112
	v_mul_f32_e32 v89, v108, v89
	v_mul_f32_e32 v108, v118, v109
	v_mul_f32_e32 v99, v99, v108
	v_add_f32_e32 v108, 1.0, v110
	v_mov_b32_dpp v183, v105 row_shr:1 row_mask:0xf bank_mask:0xf
	v_rcp_f32_e32 v110, v108
	v_mov_b32_dpp v116, v105 row_shr:2 row_mask:0xf bank_mask:0xf
	v_fma_f32 v108, v182, v105, v69
	v_fmac_f32_e32 v108, v77, v183
	v_mov_b32_dpp v73, v104 row_shr:1 row_mask:0xf bank_mask:0xf
	v_fma_f32 v111, v65, v116, v108
	v_mul_f32_e32 v108, v111, v111
	v_fmamk_f32 v108, v108, 0xbdd2d3e8, v206
	v_mul_f32_e32 v108, v111, v108
	v_exp_f32_e32 v112, v108
	v_mov_b32_dpp v120, v104 row_shr:2 row_mask:0xf bank_mask:0xf
	v_fma_f32 v108, v72, v104, v68
	v_fmac_f32_e32 v108, v76, v73
	v_or_b32_e32 v115, 48, v208
	v_fma_f32 v73, v64, v120, v108
	v_mul_f32_e32 v108, v73, v73
	v_fmamk_f32 v108, v108, 0xbdd2d3e8, v206
	v_mul_f32_e32 v108, v73, v108
	v_exp_f32_e32 v108, v108
	v_add_f32_e32 v109, 1.0, v112
	v_rcp_f32_e32 v109, v109
	v_mul_f32_e32 v75, v75, v110
	v_add_f32_e32 v108, 1.0, v108
	v_rcp_f32_e32 v108, v108
	v_mul_f32_e32 v75, v98, v75
	v_mul_f32_e32 v98, v111, v109
	v_mul_f32_e32 v97, v97, v98
	v_mul_f32_e32 v73, v73, v108
	v_mad_i64_i32 v[108:109], s[0:1], v115, s85, v[138:139]
	v_lshl_add_u64 v[108:109], v[108:109], 0, v[136:137]
	v_mul_f32_e32 v73, v96, v73
	v_cvt_pk_bf16_f32 v96, v73, v97
	v_cvt_pk_bf16_f32 v97, v75, v99
	v_cvt_pk_bf16_f32 v98, v89, v113
	v_cvt_pk_bf16_f32 v99, v91, v114
	global_store_dwordx4 v[108:109], v[96:99], off
	s_and_saveexec_b64 s[66:67], s[4:5]
	s_cbranch_execz .LBB0_875
	v_lshl_add_u64 v[96:97], s[64:65], 0, v[170:171]
	v_mov_b64_e32 v[98:99], s[12:13]
	v_mad_u64_u32 v[98:99], s[0:1], v96, s84, v[98:99]
	v_mad_i32_i24 v99, v97, s84, v99
	v_lshl_add_u64 v[96:97], v[180:181], 2, v[98:99]
	global_store_dwordx4 v[96:97], v[104:107], off
	global_store_dwordx4 v[96:97], v[100:103], off offset:16
.LBB0_875:
	s_or_b64 exec, exec, s[66:67]
	s_add_i32 s0, s62, 2
	s_ashr_i32 s1, s0, 31
	v_mov_b32_dpp v73, v52 row_ror:1 row_mask:0xf bank_mask:0xf
	v_mov_b32_dpp v96, v52 row_ror:2 row_mask:0xf bank_mask:0xf
	v_mov_b32_dpp v183, v53 row_ror:1 row_mask:0xf bank_mask:0xf
	v_mov_b32_dpp v97, v53 row_ror:2 row_mask:0xf bank_mask:0xf
	v_mov_b32_dpp v75, v54 row_ror:1 row_mask:0xf bank_mask:0xf
	v_mov_b32_dpp v98, v54 row_ror:2 row_mask:0xf bank_mask:0xf
	v_mov_b32_dpp v185, v55 row_ror:1 row_mask:0xf bank_mask:0xf
	v_mov_b32_dpp v99, v55 row_ror:2 row_mask:0xf bank_mask:0xf
	v_mov_b32_dpp v89, v48 row_ror:1 row_mask:0xf bank_mask:0xf
	v_mov_b32_dpp v100, v48 row_ror:2 row_mask:0xf bank_mask:0xf
	v_mov_b32_dpp v187, v49 row_ror:1 row_mask:0xf bank_mask:0xf
	v_mov_b32_dpp v101, v49 row_ror:2 row_mask:0xf bank_mask:0xf
	v_mov_b32_dpp v91, v50 row_ror:1 row_mask:0xf bank_mask:0xf
	v_mov_b32_dpp v102, v50 row_ror:2 row_mask:0xf bank_mask:0xf
	v_mov_b32_dpp v189, v51 row_ror:1 row_mask:0xf bank_mask:0xf
	v_mov_b32_dpp v103, v51 row_ror:2 row_mask:0xf bank_mask:0xf
	s_lshl_b64 s[62:63], s[0:1], 1
	v_mov_b32_dpp v73, v52 row_shr:1 row_mask:0xf bank_mask:0xf
	v_mov_b32_dpp v96, v52 row_shr:2 row_mask:0xf bank_mask:0xf
	v_mov_b32_dpp v183, v53 row_shr:1 row_mask:0xf bank_mask:0xf
	v_mov_b32_dpp v97, v53 row_shr:2 row_mask:0xf bank_mask:0xf
	v_mov_b32_dpp v75, v54 row_shr:1 row_mask:0xf bank_mask:0xf
	v_mov_b32_dpp v98, v54 row_shr:2 row_mask:0xf bank_mask:0xf
	v_mov_b32_dpp v185, v55 row_shr:1 row_mask:0xf bank_mask:0xf
	v_mov_b32_dpp v99, v55 row_shr:2 row_mask:0xf bank_mask:0xf
	v_mov_b32_dpp v89, v48 row_shr:1 row_mask:0xf bank_mask:0xf
	v_mov_b32_dpp v100, v48 row_shr:2 row_mask:0xf bank_mask:0xf
	v_mov_b32_dpp v187, v49 row_shr:1 row_mask:0xf bank_mask:0xf
	v_mov_b32_dpp v101, v49 row_shr:2 row_mask:0xf bank_mask:0xf
	v_mov_b32_dpp v91, v50 row_shr:1 row_mask:0xf bank_mask:0xf
	v_mov_b32_dpp v102, v50 row_shr:2 row_mask:0xf bank_mask:0xf
	v_mov_b32_dpp v189, v51 row_shr:1 row_mask:0xf bank_mask:0xf
	v_mov_b32_dpp v103, v51 row_shr:2 row_mask:0xf bank_mask:0xf
	s_and_saveexec_b64 s[0:1], s[2:3]
	s_xor_b64 s[64:65], exec, s[0:1]
	s_cbranch_execz .LBB0_877
	v_or_b32_e32 v73, s62, v168
	v_mov_b64_e32 v[96:97], s[14:15]
	v_mov_b64_e32 v[98:99], s[18:19]
	v_mad_u64_u32 v[96:97], s[0:1], v73, s84, v[96:97]
	v_mad_u64_u32 v[98:99], s[0:1], v73, s84, v[98:99]
	v_mad_i32_i24 v97, s63, v207, v97
	v_mad_i32_i24 v99, s63, v207, v99
	v_lshl_add_u64 v[96:97], v[96:97], 0, v[190:191]
	v_lshl_add_u64 v[98:99], v[98:99], 0, v[190:191]
	global_store_dwordx4 v[96:97], v[52:55], off
	global_store_dwordx4 v[96:97], v[48:51], off offset:16
	global_store_dwordx4 v[98:99], v[56:59], off
	global_store_dwordx4 v[98:99], v[60:63], off offset:16
.LBB0_877:
	s_andn2_saveexec_b64 s[64:65], s[64:65]
	s_cbranch_execz .LBB0_879
	v_fma_f32 v104, v188, v51, v87
	v_fmac_f32_e32 v104, v95, v189
	s_nop 0
	v_fma_f32 v103, v83, v103, v104
	v_mul_f32_e32 v104, v103, v103
	v_fmamk_f32 v104, v104, 0xbdd2d3e8, v206
	v_mul_f32_e32 v104, v103, v104
	v_exp_f32_e32 v106, v104
	v_fma_f32 v104, v90, v50, v86
	v_fmac_f32_e32 v104, v94, v91
	s_nop 0
	v_fma_f32 v91, v82, v102, v104
	v_mul_f32_e32 v102, v91, v91
	v_fmamk_f32 v102, v102, 0xbdd2d3e8, v206
	v_mul_f32_e32 v102, v91, v102
	v_exp_f32_e32 v102, v102
	v_add_f32_e32 v104, 1.0, v106
	v_rcp_f32_e32 v104, v104
	v_add_f32_e32 v102, 1.0, v102
	v_rcp_f32_e32 v102, v102
	v_mul_f32_e32 v103, v103, v104
	v_mul_f32_e32 v104, v63, v103
	v_mul_f32_e32 v63, v91, v102
	v_fma_f32 v102, v186, v49, v85
	v_fmac_f32_e32 v102, v93, v187
	s_nop 0
	v_fma_f32 v91, v81, v101, v102
	v_fma_f32 v102, v88, v48, v84
	v_fmac_f32_e32 v102, v92, v89
	v_fma_f32 v89, v80, v100, v102
	v_mul_f32_e32 v101, v91, v91
	v_fmamk_f32 v101, v101, 0xbdd2d3e8, v206
	v_mul_f32_e32 v100, v89, v89
	v_mul_f32_e32 v101, v91, v101
	v_fmamk_f32 v100, v100, 0xbdd2d3e8, v206
	v_exp_f32_e32 v101, v101
	v_mul_f32_e32 v100, v89, v100
	v_exp_f32_e32 v100, v100
	v_mul_f32_e32 v102, v62, v63
	v_add_f32_e32 v62, 1.0, v101
	v_rcp_f32_e32 v101, v62
	v_add_f32_e32 v62, 1.0, v100
	v_rcp_f32_e32 v100, v62
	v_fma_f32 v62, v184, v55, v71
	v_fmac_f32_e32 v62, v79, v185
	s_nop 0
	v_fma_f32 v99, v67, v99, v62
	v_mul_f32_e32 v62, v99, v99
	v_fmamk_f32 v62, v62, 0xbdd2d3e8, v206
	v_mul_f32_e32 v62, v99, v62
	v_exp_f32_e32 v62, v62
	v_mul_f32_e32 v63, v91, v101
	v_mul_f32_e32 v91, v61, v63
	v_mul_f32_e32 v61, v89, v100
	v_add_f32_e32 v62, 1.0, v62
	v_rcp_f32_e32 v89, v62
	v_fma_f32 v62, v74, v54, v70
	v_fmac_f32_e32 v62, v78, v75
	v_mul_f32_e32 v75, v60, v61
	v_fma_f32 v62, v66, v98, v62
	v_mul_f32_e32 v63, v62, v62
	v_fmamk_f32 v63, v63, 0xbdd2d3e8, v206
	v_mul_f32_e32 v63, v62, v63
	v_exp_f32_e32 v63, v63
	v_mul_f32_e32 v60, v99, v89
	v_mul_f32_e32 v59, v59, v60
	v_add_f32_e32 v60, 1.0, v63
	v_rcp_f32_e32 v63, v60
	v_fma_f32 v60, v182, v53, v69
	v_fmac_f32_e32 v60, v77, v183
	v_mul_f32_e32 v62, v62, v63
	v_fma_f32 v89, v65, v97, v60
	v_mul_f32_e32 v60, v89, v89
	v_fmamk_f32 v60, v60, 0xbdd2d3e8, v206
	v_mul_f32_e32 v60, v89, v60
	v_exp_f32_e32 v97, v60
	v_fma_f32 v60, v72, v52, v68
	v_fmac_f32_e32 v60, v76, v73
	v_add_f32_e32 v63, 1.0, v97
	v_fma_f32 v60, v64, v96, v60
	v_mul_f32_e32 v61, v60, v60
	v_fmamk_f32 v61, v61, 0xbdd2d3e8, v206
	v_mul_f32_e32 v61, v60, v61
	v_exp_f32_e32 v61, v61
	v_rcp_f32_e32 v63, v63
	v_mul_f32_e32 v58, v58, v62
	v_add_f32_e32 v61, 1.0, v61
	v_rcp_f32_e32 v61, v61
	v_mul_f32_e32 v62, v89, v63
	v_mul_f32_e32 v57, v57, v62
	v_add_u32_e32 v62, 0x80, v208
	v_mul_f32_e32 v60, v60, v61
	v_mul_f32_e32 v56, v56, v60
	v_mov_b64_e32 v[60:61], s[10:11]
	v_mad_i64_i32 v[60:61], s[0:1], v62, s85, v[60:61]
	v_lshl_add_u64 v[60:61], v[180:181], 1, v[60:61]
	v_cvt_pk_bf16_f32 v56, v56, v57
	v_cvt_pk_bf16_f32 v57, v58, v59
	v_cvt_pk_bf16_f32 v58, v75, v91
	v_cvt_pk_bf16_f32 v59, v102, v104
	global_store_dwordx4 v[60:61], v[56:59], off
.LBB0_879:
	s_or_b64 exec, exec, s[64:65]
	v_mov_b32_dpp v73, v52 row_ror:1 row_mask:0xf bank_mask:0xf
	v_mov_b32_dpp v56, v52 row_ror:2 row_mask:0xf bank_mask:0xf
	v_mov_b32_dpp v183, v53 row_ror:1 row_mask:0xf bank_mask:0xf
	v_mov_b32_dpp v52, v53 row_ror:2 row_mask:0xf bank_mask:0xf
	v_mov_b32_dpp v75, v54 row_ror:1 row_mask:0xf bank_mask:0xf
	v_mov_b32_dpp v53, v54 row_ror:2 row_mask:0xf bank_mask:0xf
	v_mov_b32_dpp v185, v55 row_ror:1 row_mask:0xf bank_mask:0xf
	v_mov_b32_dpp v54, v55 row_ror:2 row_mask:0xf bank_mask:0xf
	v_mov_b32_dpp v91, v50 row_ror:1 row_mask:0xf bank_mask:0xf
	v_mov_b32_dpp v58, v50 row_ror:2 row_mask:0xf bank_mask:0xf
	v_mov_b32_dpp v189, v51 row_ror:1 row_mask:0xf bank_mask:0xf
	v_mov_b32_dpp v89, v48 row_ror:1 row_mask:0xf bank_mask:0xf
	v_mov_b32_dpp v55, v48 row_ror:2 row_mask:0xf bank_mask:0xf
	v_mov_b32_dpp v187, v49 row_ror:1 row_mask:0xf bank_mask:0xf
	v_mov_b32_dpp v57, v49 row_ror:2 row_mask:0xf bank_mask:0xf
	v_mov_b32_dpp v189, v35 row_shr:1 row_mask:0xf bank_mask:0xf
	v_mov_b32_dpp v50, v51 row_ror:2 row_mask:0xf bank_mask:0xf
	v_mov_b32_dpp v50, v35 row_shr:2 row_mask:0xf bank_mask:0xf
	v_fma_f32 v48, v188, v35, v87
	v_fmac_f32_e32 v48, v95, v189
	v_mov_b32_dpp v91, v34 row_shr:1 row_mask:0xf bank_mask:0xf
	v_fma_f32 v50, v83, v50, v48
	v_mul_f32_e32 v48, v50, v50
	v_fmamk_f32 v48, v48, 0xbdd2d3e8, v206
	v_mul_f32_e32 v48, v50, v48
	v_exp_f32_e32 v51, v48
	v_mov_b32_dpp v58, v34 row_shr:2 row_mask:0xf bank_mask:0xf
	v_fma_f32 v48, v90, v34, v86
	v_fmac_f32_e32 v48, v94, v91
	v_add_f32_e32 v51, 1.0, v51
	v_fma_f32 v48, v82, v58, v48
	v_mul_f32_e32 v49, v48, v48
	v_fmamk_f32 v49, v49, 0xbdd2d3e8, v206
	v_mul_f32_e32 v49, v48, v49
	v_exp_f32_e32 v49, v49
	v_rcp_f32_e32 v51, v51
	v_mov_b32_dpp v187, v33 row_shr:1 row_mask:0xf bank_mask:0xf
	v_mov_b32_dpp v57, v33 row_shr:2 row_mask:0xf bank_mask:0xf
	v_add_f32_e32 v49, 1.0, v49
	v_rcp_f32_e32 v49, v49
	v_mul_f32_e32 v50, v50, v51
	v_mul_f32_e32 v50, v47, v50
	v_mov_b32_dpp v89, v32 row_shr:1 row_mask:0xf bank_mask:0xf
	v_mul_f32_e32 v47, v48, v49
	v_fma_f32 v48, v186, v33, v85
	v_fmac_f32_e32 v48, v93, v187
	v_mov_b32_dpp v55, v32 row_shr:2 row_mask:0xf bank_mask:0xf
	v_fma_f32 v51, v81, v57, v48
	v_mul_f32_e32 v48, v51, v51
	v_fmamk_f32 v48, v48, 0xbdd2d3e8, v206
	v_mul_f32_e32 v48, v51, v48
	v_exp_f32_e32 v57, v48
	v_fma_f32 v48, v88, v32, v84
	v_fmac_f32_e32 v48, v92, v89
	v_mov_b32_dpp v185, v39 row_shr:1 row_mask:0xf bank_mask:0xf
	v_fma_f32 v48, v80, v55, v48
	v_mul_f32_e32 v49, v48, v48
	v_fmamk_f32 v49, v49, 0xbdd2d3e8, v206
	v_mul_f32_e32 v49, v48, v49
	v_exp_f32_e32 v49, v49
	v_mul_f32_e32 v55, v46, v47
	v_add_f32_e32 v46, 1.0, v57
	v_rcp_f32_e32 v57, v46
	v_add_f32_e32 v46, 1.0, v49
	v_rcp_f32_e32 v49, v46
	v_mov_b32_dpp v54, v39 row_shr:2 row_mask:0xf bank_mask:0xf
	v_fma_f32 v46, v184, v39, v71
	v_fmac_f32_e32 v46, v79, v185
	v_mov_b32_dpp v75, v38 row_shr:1 row_mask:0xf bank_mask:0xf
	v_fma_f32 v54, v67, v54, v46
	v_mul_f32_e32 v46, v54, v54
	v_fmamk_f32 v46, v46, 0xbdd2d3e8, v206
	v_mul_f32_e32 v46, v54, v46
	v_exp_f32_e32 v46, v46
	v_mul_f32_e32 v47, v51, v57
	v_mul_f32_e32 v51, v45, v47
	v_mul_f32_e32 v45, v48, v49
	v_add_f32_e32 v46, 1.0, v46
	v_rcp_f32_e32 v48, v46
	v_mov_b32_dpp v53, v38 row_shr:2 row_mask:0xf bank_mask:0xf
	v_fma_f32 v46, v74, v38, v70
	v_fmac_f32_e32 v46, v78, v75
	v_mul_f32_e32 v49, v44, v45
	v_fma_f32 v46, v66, v53, v46
	v_mul_f32_e32 v47, v46, v46
	v_fmamk_f32 v47, v47, 0xbdd2d3e8, v206
	v_mul_f32_e32 v47, v46, v47
	v_exp_f32_e32 v47, v47
	v_mul_f32_e32 v44, v54, v48
	v_mul_f32_e32 v43, v43, v44
	v_mov_b32_dpp v183, v37 row_shr:1 row_mask:0xf bank_mask:0xf
	v_add_f32_e32 v44, 1.0, v47
	v_rcp_f32_e32 v47, v44
	v_mov_b32_dpp v52, v37 row_shr:2 row_mask:0xf bank_mask:0xf
	v_fma_f32 v44, v182, v37, v69
	v_fmac_f32_e32 v44, v77, v183
	v_mov_b32_dpp v73, v36 row_shr:1 row_mask:0xf bank_mask:0xf
	v_fma_f32 v48, v65, v52, v44
	v_mul_f32_e32 v44, v48, v48
	v_fmamk_f32 v44, v44, 0xbdd2d3e8, v206
	v_mul_f32_e32 v44, v48, v44
	v_exp_f32_e32 v52, v44
	v_mov_b32_dpp v56, v36 row_shr:2 row_mask:0xf bank_mask:0xf
	v_fma_f32 v44, v72, v36, v68
	v_fmac_f32_e32 v44, v76, v73
	v_mul_f32_e32 v46, v46, v47
	v_fma_f32 v44, v64, v56, v44
	v_mul_f32_e32 v45, v44, v44
	v_fmamk_f32 v45, v45, 0xbdd2d3e8, v206
	v_mul_f32_e32 v45, v44, v45
	v_exp_f32_e32 v45, v45
	v_add_f32_e32 v47, 1.0, v52
	v_rcp_f32_e32 v47, v47
	v_mul_f32_e32 v46, v42, v46
	v_add_f32_e32 v45, 1.0, v45
	v_rcp_f32_e32 v45, v45
	v_mul_f32_e32 v42, v48, v47
	v_mul_f32_e32 v41, v41, v42
	v_add_u32_e32 v58, 0x90, v208
	v_mul_f32_e32 v42, v44, v45
	v_mul_f32_e32 v40, v40, v42
	v_cvt_pk_bf16_f32 v42, v40, v41
	v_mov_b64_e32 v[40:41], s[10:11]
	v_cvt_pk_bf16_f32 v43, v46, v43
	v_mad_i64_i32 v[46:47], s[0:1], v58, s85, v[40:41]
	v_lshl_add_u64 v[46:47], v[46:47], 0, v[136:137]
	v_cvt_pk_bf16_f32 v44, v49, v51
	v_cvt_pk_bf16_f32 v45, v55, v50
	global_store_dwordx4 v[46:47], v[42:45], off
	v_mov_b32_dpp v73, v36 row_ror:1 row_mask:0xf bank_mask:0xf
	v_mov_b32_dpp v183, v37 row_ror:1 row_mask:0xf bank_mask:0xf
	v_mov_b32_dpp v42, v36 row_ror:2 row_mask:0xf bank_mask:0xf
	v_mov_b32_dpp v36, v37 row_ror:2 row_mask:0xf bank_mask:0xf
	v_mov_b32_dpp v75, v38 row_ror:1 row_mask:0xf bank_mask:0xf
	v_mov_b32_dpp v37, v38 row_ror:2 row_mask:0xf bank_mask:0xf
	v_mov_b32_dpp v185, v39 row_ror:1 row_mask:0xf bank_mask:0xf
	v_mov_b32_dpp v38, v39 row_ror:2 row_mask:0xf bank_mask:0xf
	v_mov_b32_dpp v91, v34 row_ror:1 row_mask:0xf bank_mask:0xf
	v_mov_b32_dpp v44, v34 row_ror:2 row_mask:0xf bank_mask:0xf
	v_mov_b32_dpp v189, v35 row_ror:1 row_mask:0xf bank_mask:0xf
	v_mov_b32_dpp v89, v32 row_ror:1 row_mask:0xf bank_mask:0xf
	v_mov_b32_dpp v39, v32 row_ror:2 row_mask:0xf bank_mask:0xf
	v_mov_b32_dpp v187, v33 row_ror:1 row_mask:0xf bank_mask:0xf
	v_mov_b32_dpp v43, v33 row_ror:2 row_mask:0xf bank_mask:0xf
	v_mov_b32_dpp v189, v19 row_shr:1 row_mask:0xf bank_mask:0xf
	v_mov_b32_dpp v34, v35 row_ror:2 row_mask:0xf bank_mask:0xf
	v_mov_b32_dpp v34, v19 row_shr:2 row_mask:0xf bank_mask:0xf
	v_fma_f32 v32, v188, v19, v87
	v_fmac_f32_e32 v32, v95, v189
	v_mov_b32_dpp v91, v18 row_shr:1 row_mask:0xf bank_mask:0xf
	v_fma_f32 v34, v83, v34, v32
	v_mul_f32_e32 v32, v34, v34
	v_fmamk_f32 v32, v32, 0xbdd2d3e8, v206
	v_mul_f32_e32 v32, v34, v32
	v_exp_f32_e32 v35, v32
	v_mov_b32_dpp v44, v18 row_shr:2 row_mask:0xf bank_mask:0xf
	v_fma_f32 v32, v90, v18, v86
	v_fmac_f32_e32 v32, v94, v91
	v_add_f32_e32 v35, 1.0, v35
	v_fma_f32 v32, v82, v44, v32
	v_mul_f32_e32 v33, v32, v32
	v_fmamk_f32 v33, v33, 0xbdd2d3e8, v206
	v_mul_f32_e32 v33, v32, v33
	v_exp_f32_e32 v33, v33
	v_rcp_f32_e32 v35, v35
	v_mov_b32_dpp v187, v17 row_shr:1 row_mask:0xf bank_mask:0xf
	v_mov_b32_dpp v43, v17 row_shr:2 row_mask:0xf bank_mask:0xf
	v_add_f32_e32 v33, 1.0, v33
	v_rcp_f32_e32 v33, v33
	v_mul_f32_e32 v34, v34, v35
	v_mul_f32_e32 v34, v31, v34
	v_mov_b32_dpp v89, v16 row_shr:1 row_mask:0xf bank_mask:0xf
	v_mul_f32_e32 v31, v32, v33
	v_fma_f32 v32, v186, v17, v85
	v_fmac_f32_e32 v32, v93, v187
	v_mov_b32_dpp v39, v16 row_shr:2 row_mask:0xf bank_mask:0xf
	v_fma_f32 v35, v81, v43, v32
	v_mul_f32_e32 v32, v35, v35
	v_fmamk_f32 v32, v32, 0xbdd2d3e8, v206
	v_mul_f32_e32 v32, v35, v32
	v_exp_f32_e32 v43, v32
	v_fma_f32 v32, v88, v16, v84
	v_fmac_f32_e32 v32, v92, v89
	v_mov_b32_dpp v185, v23 row_shr:1 row_mask:0xf bank_mask:0xf
	v_fma_f32 v32, v80, v39, v32
	v_mul_f32_e32 v33, v32, v32
	v_fmamk_f32 v33, v33, 0xbdd2d3e8, v206
	v_mul_f32_e32 v33, v32, v33
	v_exp_f32_e32 v33, v33
	v_mul_f32_e32 v39, v30, v31
	v_add_f32_e32 v30, 1.0, v43
	v_rcp_f32_e32 v43, v30
	v_add_f32_e32 v30, 1.0, v33
	v_rcp_f32_e32 v33, v30
	v_mov_b32_dpp v38, v23 row_shr:2 row_mask:0xf bank_mask:0xf
	v_fma_f32 v30, v184, v23, v71
	v_fmac_f32_e32 v30, v79, v185
	v_mov_b32_dpp v75, v22 row_shr:1 row_mask:0xf bank_mask:0xf
	v_fma_f32 v38, v67, v38, v30
	v_mul_f32_e32 v30, v38, v38
	v_fmamk_f32 v30, v30, 0xbdd2d3e8, v206
	v_mul_f32_e32 v30, v38, v30
	v_exp_f32_e32 v30, v30
	v_mul_f32_e32 v31, v35, v43
	v_mul_f32_e32 v35, v29, v31
	v_mul_f32_e32 v29, v32, v33
	v_add_f32_e32 v30, 1.0, v30
	v_rcp_f32_e32 v32, v30
	v_mov_b32_dpp v37, v22 row_shr:2 row_mask:0xf bank_mask:0xf
	v_fma_f32 v30, v74, v22, v70
	v_fmac_f32_e32 v30, v78, v75
	v_mul_f32_e32 v33, v28, v29
	v_fma_f32 v30, v66, v37, v30
	v_mul_f32_e32 v31, v30, v30
	v_fmamk_f32 v31, v31, 0xbdd2d3e8, v206
	v_mul_f32_e32 v31, v30, v31
	v_exp_f32_e32 v31, v31
	v_mul_f32_e32 v28, v38, v32
	v_mul_f32_e32 v27, v27, v28
	v_mov_b32_dpp v183, v21 row_shr:1 row_mask:0xf bank_mask:0xf
	v_add_f32_e32 v28, 1.0, v31
	v_rcp_f32_e32 v31, v28
	v_mov_b32_dpp v36, v21 row_shr:2 row_mask:0xf bank_mask:0xf
	v_fma_f32 v28, v182, v21, v69
	v_fmac_f32_e32 v28, v77, v183
	v_mov_b32_dpp v73, v20 row_shr:1 row_mask:0xf bank_mask:0xf
	v_fma_f32 v32, v65, v36, v28
	v_mul_f32_e32 v28, v32, v32
	v_fmamk_f32 v28, v28, 0xbdd2d3e8, v206
	v_mul_f32_e32 v28, v32, v28
	v_exp_f32_e32 v36, v28
	v_mov_b32_dpp v42, v20 row_shr:2 row_mask:0xf bank_mask:0xf
	v_fma_f32 v28, v72, v20, v68
	v_fmac_f32_e32 v28, v76, v73
	v_mul_f32_e32 v30, v30, v31
	v_fma_f32 v28, v64, v42, v28
	v_mul_f32_e32 v29, v28, v28
	v_fmamk_f32 v29, v29, 0xbdd2d3e8, v206
	v_mul_f32_e32 v29, v28, v29
	v_exp_f32_e32 v29, v29
	v_add_f32_e32 v31, 1.0, v36
	v_rcp_f32_e32 v31, v31
	v_add_u32_e32 v44, 0xa0, v208
	v_add_f32_e32 v29, 1.0, v29
	v_rcp_f32_e32 v29, v29
	v_mul_f32_e32 v26, v26, v30
	v_mul_f32_e32 v30, v32, v31
	v_mul_f32_e32 v25, v25, v30
	v_mul_f32_e32 v28, v28, v29
	v_mul_f32_e32 v24, v24, v28
	v_mad_i64_i32 v[28:29], s[0:1], v44, s85, v[40:41]
	v_cvt_pk_bf16_f32 v24, v24, v25
	v_lshl_add_u64 v[28:29], v[28:29], 0, v[136:137]
	v_cvt_pk_bf16_f32 v25, v26, v27
	v_cvt_pk_bf16_f32 v26, v33, v35
	v_cvt_pk_bf16_f32 v27, v39, v34
	global_store_dwordx4 v[28:29], v[24:27], off
	v_mov_b32_dpp v73, v20 row_ror:1 row_mask:0xf bank_mask:0xf
	v_mov_b32_dpp v183, v21 row_ror:1 row_mask:0xf bank_mask:0xf
	v_mov_b32_dpp v24, v20 row_ror:2 row_mask:0xf bank_mask:0xf
	v_mov_b32_dpp v20, v21 row_ror:2 row_mask:0xf bank_mask:0xf
	v_mov_b32_dpp v75, v22 row_ror:1 row_mask:0xf bank_mask:0xf
	v_mov_b32_dpp v21, v22 row_ror:2 row_mask:0xf bank_mask:0xf
	v_mov_b32_dpp v185, v23 row_ror:1 row_mask:0xf bank_mask:0xf
	v_mov_b32_dpp v22, v23 row_ror:2 row_mask:0xf bank_mask:0xf
	v_mov_b32_dpp v91, v18 row_ror:1 row_mask:0xf bank_mask:0xf
	v_mov_b32_dpp v26, v18 row_ror:2 row_mask:0xf bank_mask:0xf
	v_mov_b32_dpp v189, v19 row_ror:1 row_mask:0xf bank_mask:0xf
	v_mov_b32_dpp v89, v16 row_ror:1 row_mask:0xf bank_mask:0xf
	v_mov_b32_dpp v23, v16 row_ror:2 row_mask:0xf bank_mask:0xf
	v_mov_b32_dpp v187, v17 row_ror:1 row_mask:0xf bank_mask:0xf
	v_mov_b32_dpp v25, v17 row_ror:2 row_mask:0xf bank_mask:0xf
	v_mov_b32_dpp v189, v7 row_shr:1 row_mask:0xf bank_mask:0xf
	v_mov_b32_dpp v18, v19 row_ror:2 row_mask:0xf bank_mask:0xf
	v_mov_b32_dpp v18, v7 row_shr:2 row_mask:0xf bank_mask:0xf
	v_fma_f32 v16, v188, v7, v87
	v_fmac_f32_e32 v16, v95, v189
	v_mov_b32_dpp v91, v6 row_shr:1 row_mask:0xf bank_mask:0xf
	v_fma_f32 v18, v83, v18, v16
	v_mul_f32_e32 v16, v18, v18
	v_fmamk_f32 v16, v16, 0xbdd2d3e8, v206
	v_mul_f32_e32 v16, v18, v16
	v_exp_f32_e32 v19, v16
	v_mov_b32_dpp v26, v6 row_shr:2 row_mask:0xf bank_mask:0xf
	v_fma_f32 v16, v90, v6, v86
	v_fmac_f32_e32 v16, v94, v91
	v_add_f32_e32 v19, 1.0, v19
	v_fma_f32 v16, v82, v26, v16
	v_mul_f32_e32 v17, v16, v16
	v_fmamk_f32 v17, v17, 0xbdd2d3e8, v206
	v_mul_f32_e32 v17, v16, v17
	v_exp_f32_e32 v17, v17
	v_rcp_f32_e32 v19, v19
	v_mov_b32_dpp v187, v5 row_shr:1 row_mask:0xf bank_mask:0xf
	v_mov_b32_dpp v25, v5 row_shr:2 row_mask:0xf bank_mask:0xf
	v_add_f32_e32 v17, 1.0, v17
	v_rcp_f32_e32 v17, v17
	v_mul_f32_e32 v18, v18, v19
	v_mul_f32_e32 v18, v15, v18
	v_mov_b32_dpp v89, v4 row_shr:1 row_mask:0xf bank_mask:0xf
	v_mul_f32_e32 v15, v16, v17
	v_fma_f32 v16, v186, v5, v85
	v_fmac_f32_e32 v16, v93, v187
	v_mov_b32_dpp v23, v4 row_shr:2 row_mask:0xf bank_mask:0xf
	v_fma_f32 v19, v81, v25, v16
	v_mul_f32_e32 v16, v19, v19
	v_fmamk_f32 v16, v16, 0xbdd2d3e8, v206
	v_mul_f32_e32 v16, v19, v16
	v_exp_f32_e32 v25, v16
	v_fma_f32 v16, v88, v4, v84
	v_fmac_f32_e32 v16, v92, v89
	v_mov_b32_dpp v185, v11 row_shr:1 row_mask:0xf bank_mask:0xf
	v_fma_f32 v16, v80, v23, v16
	v_mul_f32_e32 v17, v16, v16
	v_fmamk_f32 v17, v17, 0xbdd2d3e8, v206
	v_mul_f32_e32 v17, v16, v17
	v_exp_f32_e32 v17, v17
	v_mul_f32_e32 v23, v14, v15
	v_add_f32_e32 v14, 1.0, v25
	v_rcp_f32_e32 v25, v14
	v_add_f32_e32 v14, 1.0, v17
	v_rcp_f32_e32 v17, v14
	v_mov_b32_dpp v22, v11 row_shr:2 row_mask:0xf bank_mask:0xf
	v_fma_f32 v14, v184, v11, v71
	v_fmac_f32_e32 v14, v79, v185
	v_mov_b32_dpp v75, v10 row_shr:1 row_mask:0xf bank_mask:0xf
	v_fma_f32 v22, v67, v22, v14
	v_mul_f32_e32 v14, v22, v22
	v_fmamk_f32 v14, v14, 0xbdd2d3e8, v206
	v_mul_f32_e32 v14, v22, v14
	v_exp_f32_e32 v14, v14
	v_mul_f32_e32 v15, v19, v25
	v_mul_f32_e32 v19, v13, v15
	v_mul_f32_e32 v13, v16, v17
	v_add_f32_e32 v14, 1.0, v14
	v_rcp_f32_e32 v16, v14
	v_mov_b32_dpp v21, v10 row_shr:2 row_mask:0xf bank_mask:0xf
	v_fma_f32 v14, v74, v10, v70
	v_fmac_f32_e32 v14, v78, v75
	v_mul_f32_e32 v17, v12, v13
	v_fma_f32 v14, v66, v21, v14
	v_mul_f32_e32 v15, v14, v14
	v_fmamk_f32 v15, v15, 0xbdd2d3e8, v206
	v_mul_f32_e32 v15, v14, v15
	v_exp_f32_e32 v15, v15
	v_mul_f32_e32 v12, v22, v16
	v_mul_f32_e32 v3, v3, v12
	v_mov_b32_dpp v183, v9 row_shr:1 row_mask:0xf bank_mask:0xf
	v_add_f32_e32 v12, 1.0, v15
	v_rcp_f32_e32 v15, v12
	v_mov_b32_dpp v20, v9 row_shr:2 row_mask:0xf bank_mask:0xf
	v_fma_f32 v12, v182, v9, v69
	v_fmac_f32_e32 v12, v77, v183
	v_mov_b32_dpp v73, v8 row_shr:1 row_mask:0xf bank_mask:0xf
	v_fma_f32 v16, v65, v20, v12
	v_mul_f32_e32 v12, v16, v16
	v_fmamk_f32 v12, v12, 0xbdd2d3e8, v206
	v_mul_f32_e32 v12, v16, v12
	v_exp_f32_e32 v20, v12
	v_mov_b32_dpp v24, v8 row_shr:2 row_mask:0xf bank_mask:0xf
	v_fma_f32 v12, v72, v8, v68
	v_fmac_f32_e32 v12, v76, v73
	v_mul_f32_e32 v14, v14, v15
	v_fma_f32 v12, v64, v24, v12
	v_mul_f32_e32 v13, v12, v12
	v_fmamk_f32 v13, v13, 0xbdd2d3e8, v206
	v_mul_f32_e32 v13, v12, v13
	v_exp_f32_e32 v13, v13
	v_add_f32_e32 v15, 1.0, v20
	v_rcp_f32_e32 v15, v15
	v_add_u32_e32 v26, 0xb0, v208
	v_add_f32_e32 v13, 1.0, v13
	v_rcp_f32_e32 v13, v13
	v_mul_f32_e32 v2, v2, v14
	v_mul_f32_e32 v14, v16, v15
	v_mul_f32_e32 v1, v1, v14
	v_mul_f32_e32 v12, v12, v13
	v_mul_f32_e32 v0, v0, v12
	v_mad_i64_i32 v[12:13], s[0:1], v26, s85, v[40:41]
	v_lshl_add_u64 v[12:13], v[12:13], 0, v[136:137]
	v_cvt_pk_bf16_f32 v0, v0, v1
	v_cvt_pk_bf16_f32 v1, v2, v3
	v_cvt_pk_bf16_f32 v2, v17, v19
	v_cvt_pk_bf16_f32 v3, v23, v18
	global_store_dwordx4 v[12:13], v[0:3], off
	s_and_saveexec_b64 s[64:65], s[4:5]
	s_cbranch_execz .LBB0_881
	v_lshl_add_u64 v[0:1], s[62:63], 0, v[170:171]
	v_mov_b64_e32 v[2:3], s[12:13]
	v_mad_u64_u32 v[2:3], s[0:1], v0, s84, v[2:3]
	v_mad_i32_i24 v3, v1, s84, v3
	v_lshl_add_u64 v[0:1], v[180:181], 2, v[2:3]
	global_store_dwordx4 v[0:1], v[8:11], off
	global_store_dwordx4 v[0:1], v[4:7], off offset:16

.LBB0_1555:
	v_lshl_or_b32 v180, s1, 7, v202
	v_ashrrev_i32_e32 v181, 31, v180
	v_lshlrev_b64 v[190:191], 2, v[180:181]
	v_lshl_add_u64 v[68:69], s[12:13], 0, v[190:191]
	v_lshl_add_u64 v[70:71], s[44:45], 0, v[190:191]
	v_lshl_add_u64 v[72:73], s[50:51], 0, v[190:191]
	v_lshl_add_u64 v[84:85], s[14:15], 0, v[190:191]
	global_load_dwordx4 v[64:67], v[68:69], off
	global_load_dwordx4 v[80:83], v[68:69], off offset:16
	global_load_dwordx4 v[92:95], v[70:71], off offset:16
	global_load_dwordx4 v[76:79], v[70:71], off
	global_load_dwordx4 v[88:91], v[72:73], off offset:16
	s_nop 0
	global_load_dwordx4 v[72:75], v[72:73], off
	s_nop 0
	global_load_dwordx4 v[68:71], v[84:85], off
	s_nop 0
	global_load_dwordx4 v[84:87], v[84:85], off offset:16
	s_lshl_b32 s1, s0, 2
	s_add_i32 s60, s1, s69
	s_ashr_i32 s61, s60, 31
	v_mov_b32_dpp v183, v148 row_ror:1 row_mask:0xf bank_mask:0xf
	v_mov_b32_dpp v209, v148 row_ror:2 row_mask:0xf bank_mask:0xf
	v_mov_b32_dpp v185, v149 row_ror:1 row_mask:0xf bank_mask:0xf
	v_mov_b32_dpp v210, v149 row_ror:2 row_mask:0xf bank_mask:0xf
	v_mov_b32_dpp v187, v150 row_ror:1 row_mask:0xf bank_mask:0xf
	v_mov_b32_dpp v211, v150 row_ror:2 row_mask:0xf bank_mask:0xf
	v_mov_b32_dpp v189, v151 row_ror:1 row_mask:0xf bank_mask:0xf
	v_mov_b32_dpp v212, v151 row_ror:2 row_mask:0xf bank_mask:0xf
	v_mov_b32_dpp v193, v144 row_ror:1 row_mask:0xf bank_mask:0xf
	v_mov_b32_dpp v213, v144 row_ror:2 row_mask:0xf bank_mask:0xf
	v_mov_b32_dpp v195, v145 row_ror:1 row_mask:0xf bank_mask:0xf
	v_mov_b32_dpp v192, v145 row_ror:2 row_mask:0xf bank_mask:0xf
	v_mov_b32_dpp v197, v146 row_ror:1 row_mask:0xf bank_mask:0xf
	v_mov_b32_dpp v194, v146 row_ror:2 row_mask:0xf bank_mask:0xf
	v_mov_b32_dpp v199, v147 row_ror:1 row_mask:0xf bank_mask:0xf
	v_mov_b32_dpp v196, v147 row_ror:2 row_mask:0xf bank_mask:0xf
	s_lshl_b64 s[62:63], s[60:61], 1
	v_mov_b32_dpp v183, v148 row_shr:1 row_mask:0xf bank_mask:0xf
	v_mov_b32_dpp v209, v148 row_shr:2 row_mask:0xf bank_mask:0xf
	v_mov_b32_dpp v185, v149 row_shr:1 row_mask:0xf bank_mask:0xf
	v_mov_b32_dpp v210, v149 row_shr:2 row_mask:0xf bank_mask:0xf
	v_mov_b32_dpp v187, v150 row_shr:1 row_mask:0xf bank_mask:0xf
	v_mov_b32_dpp v211, v150 row_shr:2 row_mask:0xf bank_mask:0xf
	v_mov_b32_dpp v189, v151 row_shr:1 row_mask:0xf bank_mask:0xf
	v_mov_b32_dpp v212, v151 row_shr:2 row_mask:0xf bank_mask:0xf
	v_mov_b32_dpp v193, v144 row_shr:1 row_mask:0xf bank_mask:0xf
	v_mov_b32_dpp v213, v144 row_shr:2 row_mask:0xf bank_mask:0xf
	v_mov_b32_dpp v195, v145 row_shr:1 row_mask:0xf bank_mask:0xf
	v_mov_b32_dpp v192, v145 row_shr:2 row_mask:0xf bank_mask:0xf
	v_mov_b32_dpp v197, v146 row_shr:1 row_mask:0xf bank_mask:0xf
	v_mov_b32_dpp v194, v146 row_shr:2 row_mask:0xf bank_mask:0xf
	v_mov_b32_dpp v199, v147 row_shr:1 row_mask:0xf bank_mask:0xf
	v_mov_b32_dpp v196, v147 row_shr:2 row_mask:0xf bank_mask:0xf
	s_and_saveexec_b64 s[64:65], s[2:3]
	s_xor_b64 s[64:65], exec, s[64:65]
	s_cbranch_execz .LBB0_1557
	v_or_b32_e32 v186, s62, v168
	v_mov_b64_e32 v[182:183], s[20:21]
	v_mov_b64_e32 v[184:185], s[34:35]
	v_mad_u64_u32 v[182:183], s[84:85], v186, s82, v[182:183]
	v_mad_u64_u32 v[184:185], s[84:85], v186, s82, v[184:185]
	v_mad_i32_i24 v183, s63, v207, v183
	v_mad_i32_i24 v185, s63, v207, v185
	v_lshl_add_u64 v[182:183], v[182:183], 0, v[190:191]
	v_lshl_add_u64 v[184:185], v[184:185], 0, v[190:191]
	global_store_dwordx4 v[182:183], v[148:151], off
	global_store_dwordx4 v[182:183], v[144:147], off offset:16
	global_store_dwordx4 v[184:185], v[152:155], off
	global_store_dwordx4 v[184:185], v[156:159], off offset:16
	s_waitcnt vmcnt(0)
	v_mov_b32_e32 v188, v91
	v_mov_b32_e32 v186, v89
	v_mov_b32_e32 v184, v75
	v_mov_b32_e32 v182, v73
.LBB0_1557:
	s_or_saveexec_b64 s[64:65], s[64:65]
	v_lshl_add_u32 v208, s0, 8, v169
	s_xor_b64 exec, exec, s[64:65]
	s_cbranch_execz .LBB0_1559
	v_mov_b32_e32 v214, v147
	s_waitcnt vmcnt(0)
	v_mov_b32_e32 v215, v95
	v_mov_b32_e32 v198, v91
	v_pk_mul_f32 v[198:199], v[214:215], v[198:199]
	s_nop 0
	v_fma_f32 v182, v83, v196, v199
	v_add_f32_e32 v182, v198, v182
	v_add_f32_e32 v182, v87, v182
	v_mov_b32_e32 v198, v146
	v_mov_b32_e32 v199, v94
	v_mov_b32_e32 v196, v90
	v_mul_f32_e32 v184, v182, v182
	v_pk_mul_f32 v[196:197], v[198:199], v[196:197]
	v_fmamk_f32 v184, v184, 0xbdd2d3e8, v206
	v_fma_f32 v186, v82, v194, v197
	v_mul_f32_e32 v184, v182, v184
	v_add_f32_e32 v186, v196, v186
	v_exp_f32_e32 v184, v184
	v_add_f32_e32 v186, v86, v186
	v_mul_f32_e32 v188, v186, v186
	v_fmamk_f32 v188, v188, 0xbdd2d3e8, v206
	v_mul_f32_e32 v188, v186, v188
	v_exp_f32_e32 v188, v188
	v_add_f32_e32 v184, 1.0, v184
	v_rcp_f32_e32 v184, v184
	v_mov_b32_e32 v196, v145
	v_add_f32_e32 v188, 1.0, v188
	v_mov_b32_e32 v197, v93
	v_mov_b32_e32 v194, v89
	v_rcp_f32_e32 v188, v188
	v_mul_f32_e32 v182, v182, v184
	v_pk_mul_f32 v[194:195], v[196:197], v[194:195]
	v_mul_f32_e32 v198, v159, v182
	v_fma_f32 v182, v81, v192, v195
	v_add_f32_e32 v182, v194, v182
	v_mov_b32_e32 v194, v144
	v_mov_b32_e32 v195, v92
	v_mov_b32_e32 v192, v88
	v_pk_mul_f32 v[192:193], v[194:195], v[192:193]
	v_mul_f32_e32 v159, v186, v188
	v_fma_f32 v186, v80, v213, v193
	v_add_f32_e32 v182, v85, v182
	v_add_f32_e32 v186, v192, v186
	v_mul_f32_e32 v184, v182, v182
	v_add_f32_e32 v186, v84, v186
	v_fmamk_f32 v184, v184, 0xbdd2d3e8, v206
	v_mul_f32_e32 v188, v186, v186
	v_mul_f32_e32 v184, v182, v184
	v_fmamk_f32 v188, v188, 0xbdd2d3e8, v206
	v_exp_f32_e32 v184, v184
	v_mul_f32_e32 v188, v186, v188
	v_exp_f32_e32 v188, v188
	v_mul_f32_e32 v192, v158, v159
	v_add_f32_e32 v158, 1.0, v184
	v_rcp_f32_e32 v184, v158
	v_add_f32_e32 v158, 1.0, v188
	v_rcp_f32_e32 v193, v158
	v_fma_f32 v158, v75, v151, v71
	v_fmac_f32_e32 v158, v79, v189
	s_nop 0
	v_fma_f32 v188, v67, v212, v158
	v_mul_f32_e32 v158, v188, v188
	v_fmamk_f32 v158, v158, 0xbdd2d3e8, v206
	v_mul_f32_e32 v158, v188, v158
	v_exp_f32_e32 v158, v158
	v_mul_f32_e32 v159, v182, v184
	v_mul_f32_e32 v189, v157, v159
	v_mul_f32_e32 v157, v186, v193
	v_add_f32_e32 v158, 1.0, v158
	v_rcp_f32_e32 v182, v158
	v_fma_f32 v158, v74, v150, v70
	v_fmac_f32_e32 v158, v78, v187
	v_mul_f32_e32 v186, v156, v157
	v_fma_f32 v158, v66, v211, v158
	v_mul_f32_e32 v159, v158, v158
	v_fmamk_f32 v159, v159, 0xbdd2d3e8, v206
	v_mul_f32_e32 v159, v158, v159
	v_exp_f32_e32 v159, v159
	v_mul_f32_e32 v156, v188, v182
	v_mul_f32_e32 v155, v155, v156
	v_add_f32_e32 v156, 1.0, v159
	v_rcp_f32_e32 v159, v156
	v_fma_f32 v156, v73, v149, v69
	v_fmac_f32_e32 v156, v77, v185
	v_fma_f32 v184, v65, v210, v156
	v_mul_f32_e32 v156, v184, v184
	v_fmamk_f32 v156, v156, 0xbdd2d3e8, v206
	v_mul_f32_e32 v156, v184, v156
	v_exp_f32_e32 v185, v156
	v_fma_f32 v156, v72, v148, v68
	v_fmac_f32_e32 v156, v76, v183
	v_mul_f32_e32 v158, v158, v159
	v_fma_f32 v156, v64, v209, v156
	v_mul_f32_e32 v157, v156, v156
	v_fmamk_f32 v157, v157, 0xbdd2d3e8, v206
	v_mul_f32_e32 v157, v156, v157
	v_exp_f32_e32 v157, v157
	v_add_f32_e32 v159, 1.0, v185
	v_rcp_f32_e32 v159, v159
	v_mul_f32_e32 v154, v154, v158
	v_add_f32_e32 v157, 1.0, v157
	v_rcp_f32_e32 v157, v157
	v_mul_f32_e32 v158, v184, v159
	v_mul_f32_e32 v153, v153, v158
	v_mov_b32_e32 v182, v73
	v_mul_f32_e32 v156, v156, v157
	v_mul_f32_e32 v152, v152, v156
	v_mov_b64_e32 v[156:157], s[10:11]
	v_mad_i64_i32 v[156:157], s[0:1], v208, s83, v[156:157]
	v_cvt_pk_bf16_f32 v152, v152, v153
	v_cvt_pk_bf16_f32 v153, v154, v155
	v_cvt_pk_bf16_f32 v154, v186, v189
	v_lshl_add_u64 v[156:157], v[180:181], 1, v[156:157]
	v_mov_b32_e32 v184, v75
	v_mov_b32_e32 v186, v89
	v_mov_b32_e32 v188, v91
	v_cvt_pk_bf16_f32 v155, v192, v198
	global_store_dwordx4 v[156:157], v[152:155], off
.LBB0_1559:
	s_or_b64 exec, exec, s[64:65]
	s_waitcnt vmcnt(0)
	v_mov_b32_dpp v73, v148 row_ror:1 row_mask:0xf bank_mask:0xf
	v_mov_b32_dpp v152, v148 row_ror:2 row_mask:0xf bank_mask:0xf
	v_mov_b32_dpp v183, v149 row_ror:1 row_mask:0xf bank_mask:0xf
	v_mov_b32_dpp v148, v149 row_ror:2 row_mask:0xf bank_mask:0xf
	v_mov_b32_dpp v75, v150 row_ror:1 row_mask:0xf bank_mask:0xf
	v_mov_b32_dpp v149, v150 row_ror:2 row_mask:0xf bank_mask:0xf
	v_mov_b32_dpp v185, v151 row_ror:1 row_mask:0xf bank_mask:0xf
	v_mov_b32_dpp v150, v151 row_ror:2 row_mask:0xf bank_mask:0xf
	v_mov_b32_dpp v91, v146 row_ror:1 row_mask:0xf bank_mask:0xf
	v_mov_b32_dpp v154, v146 row_ror:2 row_mask:0xf bank_mask:0xf
	v_mov_b32_dpp v189, v147 row_ror:1 row_mask:0xf bank_mask:0xf
	v_mov_b32_dpp v89, v144 row_ror:1 row_mask:0xf bank_mask:0xf
	v_mov_b32_dpp v151, v144 row_ror:2 row_mask:0xf bank_mask:0xf
	v_mov_b32_dpp v187, v145 row_ror:1 row_mask:0xf bank_mask:0xf
	v_mov_b32_dpp v153, v145 row_ror:2 row_mask:0xf bank_mask:0xf
	v_mov_b32_dpp v189, v131 row_shr:1 row_mask:0xf bank_mask:0xf
	v_mov_b32_dpp v146, v147 row_ror:2 row_mask:0xf bank_mask:0xf
	v_mov_b32_dpp v146, v131 row_shr:2 row_mask:0xf bank_mask:0xf
	v_fma_f32 v144, v188, v131, v87
	v_fmac_f32_e32 v144, v95, v189
	v_mov_b32_dpp v91, v130 row_shr:1 row_mask:0xf bank_mask:0xf
	v_fma_f32 v146, v83, v146, v144
	v_mul_f32_e32 v144, v146, v146
	v_fmamk_f32 v144, v144, 0xbdd2d3e8, v206
	v_mul_f32_e32 v144, v146, v144
	v_exp_f32_e32 v147, v144
	v_mov_b32_dpp v154, v130 row_shr:2 row_mask:0xf bank_mask:0xf
	v_fma_f32 v144, v90, v130, v86
	v_fmac_f32_e32 v144, v94, v91
	v_mov_b32_dpp v187, v129 row_shr:1 row_mask:0xf bank_mask:0xf
	v_fma_f32 v91, v82, v154, v144
	v_mul_f32_e32 v144, v91, v91
	v_fmamk_f32 v144, v144, 0xbdd2d3e8, v206
	v_mul_f32_e32 v144, v91, v144
	v_exp_f32_e32 v144, v144
	v_add_f32_e32 v145, 1.0, v147
	v_rcp_f32_e32 v145, v145
	v_mov_b32_dpp v153, v129 row_shr:2 row_mask:0xf bank_mask:0xf
	v_add_f32_e32 v144, 1.0, v144
	v_rcp_f32_e32 v144, v144
	v_mul_f32_e32 v145, v146, v145
	v_mul_f32_e32 v146, v143, v145
	v_mul_f32_e32 v91, v91, v144
	v_fma_f32 v144, v186, v129, v85
	v_fmac_f32_e32 v144, v93, v187
	v_mov_b32_dpp v89, v128 row_shr:1 row_mask:0xf bank_mask:0xf
	v_fma_f32 v153, v81, v153, v144
	v_mov_b32_dpp v151, v128 row_shr:2 row_mask:0xf bank_mask:0xf
	v_fma_f32 v144, v88, v128, v84
	v_fmac_f32_e32 v144, v92, v89
	v_fma_f32 v89, v80, v151, v144
	v_mul_f32_e32 v143, v153, v153
	v_fmamk_f32 v143, v143, 0xbdd2d3e8, v206
	v_mul_f32_e32 v144, v89, v89
	v_mul_f32_e32 v143, v153, v143
	v_fmamk_f32 v144, v144, 0xbdd2d3e8, v206
	v_exp_f32_e32 v143, v143
	v_mul_f32_e32 v144, v89, v144
	v_exp_f32_e32 v144, v144
	v_mul_f32_e32 v91, v142, v91
	v_add_f32_e32 v142, 1.0, v143
	v_rcp_f32_e32 v145, v142
	v_add_f32_e32 v142, 1.0, v144
	v_mov_b32_dpp v185, v135 row_shr:1 row_mask:0xf bank_mask:0xf
	v_rcp_f32_e32 v144, v142
	v_mov_b32_dpp v150, v135 row_shr:2 row_mask:0xf bank_mask:0xf
	v_fma_f32 v142, v184, v135, v71
	v_fmac_f32_e32 v142, v79, v185
	v_mov_b32_dpp v75, v134 row_shr:1 row_mask:0xf bank_mask:0xf
	v_fma_f32 v150, v67, v150, v142
	v_mul_f32_e32 v142, v150, v150
	v_fmamk_f32 v142, v142, 0xbdd2d3e8, v206
	v_mul_f32_e32 v142, v150, v142
	v_exp_f32_e32 v142, v142
	v_mul_f32_e32 v143, v153, v145
	v_mul_f32_e32 v145, v141, v143
	v_add_f32_e32 v141, 1.0, v142
	v_mov_b32_dpp v149, v134 row_shr:2 row_mask:0xf bank_mask:0xf
	v_fma_f32 v142, v74, v134, v70
	v_fmac_f32_e32 v142, v78, v75
	v_rcp_f32_e32 v141, v141
	v_fma_f32 v75, v66, v149, v142
	v_mul_f32_e32 v142, v75, v75
	v_fmamk_f32 v142, v142, 0xbdd2d3e8, v206
	v_mul_f32_e32 v142, v75, v142
	v_exp_f32_e32 v142, v142
	v_mul_f32_e32 v89, v89, v144
	v_mul_f32_e32 v89, v140, v89
	v_mul_f32_e32 v140, v150, v141
	v_mul_f32_e32 v139, v139, v140
	v_add_f32_e32 v140, 1.0, v142
	v_mov_b32_dpp v183, v133 row_shr:1 row_mask:0xf bank_mask:0xf
	v_rcp_f32_e32 v142, v140
	v_mov_b32_dpp v148, v133 row_shr:2 row_mask:0xf bank_mask:0xf
	v_fma_f32 v140, v182, v133, v69
	v_fmac_f32_e32 v140, v77, v183
	v_mov_b32_dpp v73, v132 row_shr:1 row_mask:0xf bank_mask:0xf
	v_fma_f32 v143, v65, v148, v140
	v_mul_f32_e32 v140, v143, v143
	v_fmamk_f32 v140, v140, 0xbdd2d3e8, v206
	v_mul_f32_e32 v140, v143, v140
	v_exp_f32_e32 v144, v140
	v_mov_b32_dpp v152, v132 row_shr:2 row_mask:0xf bank_mask:0xf
	v_fma_f32 v140, v72, v132, v68
	v_fmac_f32_e32 v140, v76, v73
	v_mul_f32_e32 v75, v75, v142
	v_fma_f32 v73, v64, v152, v140
	v_mul_f32_e32 v140, v73, v73
	v_fmamk_f32 v140, v140, 0xbdd2d3e8, v206
	v_mul_f32_e32 v140, v73, v140
	v_exp_f32_e32 v140, v140
	v_add_f32_e32 v141, 1.0, v144
	v_rcp_f32_e32 v141, v141
	v_mul_f32_e32 v75, v138, v75
	v_add_f32_e32 v140, 1.0, v140
	v_rcp_f32_e32 v140, v140
	v_mul_f32_e32 v138, v143, v141
	v_or_b32_e32 v147, 16, v208
	v_mul_f32_e32 v137, v137, v138
	v_mul_f32_e32 v73, v73, v140
	v_mul_f32_e32 v73, v136, v73
	v_cvt_pk_bf16_f32 v140, v73, v137
	v_cvt_pk_bf16_f32 v141, v75, v139
	v_mov_b64_e32 v[138:139], s[10:11]
	v_cvt_pk_bf16_f32 v142, v89, v145
	v_mad_i64_i32 v[144:145], s[0:1], v147, s83, v[138:139]
	v_lshlrev_b64 v[136:137], 1, v[180:181]
	v_lshl_add_u64 v[144:145], v[144:145], 0, v[136:137]
	v_cvt_pk_bf16_f32 v143, v91, v146
	global_store_dwordx4 v[144:145], v[140:143], off
	v_mov_b32_dpp v73, v132 row_ror:1 row_mask:0xf bank_mask:0xf
	v_mov_b32_dpp v183, v133 row_ror:1 row_mask:0xf bank_mask:0xf
	v_mov_b32_dpp v140, v132 row_ror:2 row_mask:0xf bank_mask:0xf
	v_mov_b32_dpp v132, v133 row_ror:2 row_mask:0xf bank_mask:0xf
	v_mov_b32_dpp v75, v134 row_ror:1 row_mask:0xf bank_mask:0xf
	v_mov_b32_dpp v133, v134 row_ror:2 row_mask:0xf bank_mask:0xf
	v_mov_b32_dpp v185, v135 row_ror:1 row_mask:0xf bank_mask:0xf
	v_mov_b32_dpp v134, v135 row_ror:2 row_mask:0xf bank_mask:0xf
	v_mov_b32_dpp v91, v130 row_ror:1 row_mask:0xf bank_mask:0xf
	v_mov_b32_dpp v142, v130 row_ror:2 row_mask:0xf bank_mask:0xf
	v_mov_b32_dpp v189, v131 row_ror:1 row_mask:0xf bank_mask:0xf
	v_mov_b32_dpp v89, v128 row_ror:1 row_mask:0xf bank_mask:0xf
	v_mov_b32_dpp v135, v128 row_ror:2 row_mask:0xf bank_mask:0xf
	v_mov_b32_dpp v187, v129 row_ror:1 row_mask:0xf bank_mask:0xf
	v_mov_b32_dpp v141, v129 row_ror:2 row_mask:0xf bank_mask:0xf
	v_mov_b32_dpp v189, v115 row_shr:1 row_mask:0xf bank_mask:0xf
	v_mov_b32_dpp v130, v131 row_ror:2 row_mask:0xf bank_mask:0xf
	v_mov_b32_dpp v130, v115 row_shr:2 row_mask:0xf bank_mask:0xf
	v_fma_f32 v128, v188, v115, v87
	v_fmac_f32_e32 v128, v95, v189
	v_mov_b32_dpp v91, v114 row_shr:1 row_mask:0xf bank_mask:0xf
	v_fma_f32 v130, v83, v130, v128
	v_mul_f32_e32 v128, v130, v130
	v_fmamk_f32 v128, v128, 0xbdd2d3e8, v206
	v_mul_f32_e32 v128, v130, v128
	v_exp_f32_e32 v131, v128
	v_mov_b32_dpp v142, v114 row_shr:2 row_mask:0xf bank_mask:0xf
	v_fma_f32 v128, v90, v114, v86
	v_fmac_f32_e32 v128, v94, v91
	v_mov_b32_dpp v187, v113 row_shr:1 row_mask:0xf bank_mask:0xf
	v_fma_f32 v91, v82, v142, v128
	v_mul_f32_e32 v128, v91, v91
	v_fmamk_f32 v128, v128, 0xbdd2d3e8, v206
	v_mul_f32_e32 v128, v91, v128
	v_exp_f32_e32 v128, v128
	v_add_f32_e32 v129, 1.0, v131
	v_rcp_f32_e32 v129, v129
	v_mov_b32_dpp v141, v113 row_shr:2 row_mask:0xf bank_mask:0xf
	v_add_f32_e32 v128, 1.0, v128
	v_rcp_f32_e32 v128, v128
	v_mul_f32_e32 v129, v130, v129
	v_mul_f32_e32 v130, v127, v129
	v_mul_f32_e32 v91, v91, v128
	v_fma_f32 v128, v186, v113, v85
	v_fmac_f32_e32 v128, v93, v187
	v_mov_b32_dpp v89, v112 row_shr:1 row_mask:0xf bank_mask:0xf
	v_fma_f32 v141, v81, v141, v128
	v_mov_b32_dpp v135, v112 row_shr:2 row_mask:0xf bank_mask:0xf
	v_fma_f32 v128, v88, v112, v84
	v_fmac_f32_e32 v128, v92, v89
	v_fma_f32 v89, v80, v135, v128
	v_mul_f32_e32 v127, v141, v141
	v_fmamk_f32 v127, v127, 0xbdd2d3e8, v206
	v_mul_f32_e32 v128, v89, v89
	v_mul_f32_e32 v127, v141, v127
	v_fmamk_f32 v128, v128, 0xbdd2d3e8, v206
	v_exp_f32_e32 v127, v127
	v_mul_f32_e32 v128, v89, v128
	v_exp_f32_e32 v128, v128
	v_mul_f32_e32 v91, v126, v91
	v_add_f32_e32 v126, 1.0, v127
	v_rcp_f32_e32 v129, v126
	v_add_f32_e32 v126, 1.0, v128
	v_mov_b32_dpp v185, v119 row_shr:1 row_mask:0xf bank_mask:0xf
	v_rcp_f32_e32 v128, v126
	v_mov_b32_dpp v134, v119 row_shr:2 row_mask:0xf bank_mask:0xf
	v_fma_f32 v126, v184, v119, v71
	v_fmac_f32_e32 v126, v79, v185
	v_mov_b32_dpp v75, v118 row_shr:1 row_mask:0xf bank_mask:0xf
	v_fma_f32 v134, v67, v134, v126
	v_mul_f32_e32 v126, v134, v134
	v_fmamk_f32 v126, v126, 0xbdd2d3e8, v206
	v_mul_f32_e32 v126, v134, v126
	v_exp_f32_e32 v126, v126
	v_mul_f32_e32 v127, v141, v129
	v_mul_f32_e32 v129, v125, v127
	v_add_f32_e32 v125, 1.0, v126
	v_mov_b32_dpp v133, v118 row_shr:2 row_mask:0xf bank_mask:0xf
	v_fma_f32 v126, v74, v118, v70
	v_fmac_f32_e32 v126, v78, v75
	v_rcp_f32_e32 v125, v125
	v_fma_f32 v75, v66, v133, v126
	v_mul_f32_e32 v126, v75, v75
	v_fmamk_f32 v126, v126, 0xbdd2d3e8, v206
	v_mul_f32_e32 v126, v75, v126
	v_exp_f32_e32 v126, v126
	v_mul_f32_e32 v89, v89, v128
	v_mul_f32_e32 v89, v124, v89
	v_mul_f32_e32 v124, v134, v125
	v_mul_f32_e32 v123, v123, v124
	v_add_f32_e32 v124, 1.0, v126
	v_mov_b32_dpp v183, v117 row_shr:1 row_mask:0xf bank_mask:0xf
	v_rcp_f32_e32 v126, v124
	v_mov_b32_dpp v132, v117 row_shr:2 row_mask:0xf bank_mask:0xf
	v_fma_f32 v124, v182, v117, v69
	v_fmac_f32_e32 v124, v77, v183
	v_mov_b32_dpp v73, v116 row_shr:1 row_mask:0xf bank_mask:0xf
	v_fma_f32 v127, v65, v132, v124
	v_mul_f32_e32 v124, v127, v127
	v_fmamk_f32 v124, v124, 0xbdd2d3e8, v206
	v_mul_f32_e32 v124, v127, v124
	v_exp_f32_e32 v128, v124
	v_mov_b32_dpp v140, v116 row_shr:2 row_mask:0xf bank_mask:0xf
	v_fma_f32 v124, v72, v116, v68
	v_fmac_f32_e32 v124, v76, v73
	v_or_b32_e32 v131, 32, v208
	v_fma_f32 v73, v64, v140, v124
	v_mul_f32_e32 v124, v73, v73
	v_fmamk_f32 v124, v124, 0xbdd2d3e8, v206
	v_mul_f32_e32 v124, v73, v124
	v_exp_f32_e32 v124, v124
	v_add_f32_e32 v125, 1.0, v128
	v_rcp_f32_e32 v125, v125
	v_mul_f32_e32 v75, v75, v126
	v_add_f32_e32 v124, 1.0, v124
	v_rcp_f32_e32 v124, v124
	v_mul_f32_e32 v75, v122, v75
	v_mul_f32_e32 v122, v127, v125
	v_mul_f32_e32 v121, v121, v122
	v_mul_f32_e32 v73, v73, v124
	v_mad_i64_i32 v[124:125], s[0:1], v131, s83, v[138:139]
	v_mul_f32_e32 v73, v120, v73
	v_cvt_pk_bf16_f32 v120, v73, v121
	v_lshl_add_u64 v[124:125], v[124:125], 0, v[136:137]
	v_cvt_pk_bf16_f32 v121, v75, v123
	v_cvt_pk_bf16_f32 v122, v89, v129
	v_cvt_pk_bf16_f32 v123, v91, v130
	global_store_dwordx4 v[124:125], v[120:123], off
	v_mov_b32_dpp v73, v116 row_ror:1 row_mask:0xf bank_mask:0xf
	v_mov_b32_dpp v183, v117 row_ror:1 row_mask:0xf bank_mask:0xf
	v_mov_b32_dpp v120, v116 row_ror:2 row_mask:0xf bank_mask:0xf
	v_mov_b32_dpp v116, v117 row_ror:2 row_mask:0xf bank_mask:0xf
	v_mov_b32_dpp v75, v118 row_ror:1 row_mask:0xf bank_mask:0xf
	v_mov_b32_dpp v117, v118 row_ror:2 row_mask:0xf bank_mask:0xf
	v_mov_b32_dpp v185, v119 row_ror:1 row_mask:0xf bank_mask:0xf
	v_mov_b32_dpp v118, v119 row_ror:2 row_mask:0xf bank_mask:0xf
	v_mov_b32_dpp v91, v114 row_ror:1 row_mask:0xf bank_mask:0xf
	v_mov_b32_dpp v122, v114 row_ror:2 row_mask:0xf bank_mask:0xf
	v_mov_b32_dpp v189, v115 row_ror:1 row_mask:0xf bank_mask:0xf
	v_mov_b32_dpp v89, v112 row_ror:1 row_mask:0xf bank_mask:0xf
	v_mov_b32_dpp v119, v112 row_ror:2 row_mask:0xf bank_mask:0xf
	v_mov_b32_dpp v187, v113 row_ror:1 row_mask:0xf bank_mask:0xf
	v_mov_b32_dpp v121, v113 row_ror:2 row_mask:0xf bank_mask:0xf
	v_mov_b32_dpp v189, v103 row_shr:1 row_mask:0xf bank_mask:0xf
	v_mov_b32_dpp v114, v115 row_ror:2 row_mask:0xf bank_mask:0xf
	v_mov_b32_dpp v114, v103 row_shr:2 row_mask:0xf bank_mask:0xf
	v_fma_f32 v112, v188, v103, v87
	v_fmac_f32_e32 v112, v95, v189
	v_mov_b32_dpp v91, v102 row_shr:1 row_mask:0xf bank_mask:0xf
	v_fma_f32 v114, v83, v114, v112
	v_mul_f32_e32 v112, v114, v114
	v_fmamk_f32 v112, v112, 0xbdd2d3e8, v206
	v_mul_f32_e32 v112, v114, v112
	v_exp_f32_e32 v115, v112
	v_mov_b32_dpp v122, v102 row_shr:2 row_mask:0xf bank_mask:0xf
	v_fma_f32 v112, v90, v102, v86
	v_fmac_f32_e32 v112, v94, v91
	v_mov_b32_dpp v187, v101 row_shr:1 row_mask:0xf bank_mask:0xf
	v_fma_f32 v91, v82, v122, v112
	v_mul_f32_e32 v112, v91, v91
	v_fmamk_f32 v112, v112, 0xbdd2d3e8, v206
	v_mul_f32_e32 v112, v91, v112
	v_exp_f32_e32 v112, v112
	v_add_f32_e32 v113, 1.0, v115
	v_rcp_f32_e32 v113, v113
	v_mov_b32_dpp v121, v101 row_shr:2 row_mask:0xf bank_mask:0xf
	v_add_f32_e32 v112, 1.0, v112
	v_rcp_f32_e32 v112, v112
	v_mul_f32_e32 v113, v114, v113
	v_mul_f32_e32 v114, v111, v113
	v_mul_f32_e32 v91, v91, v112
	v_fma_f32 v112, v186, v101, v85
	v_fmac_f32_e32 v112, v93, v187
	v_mov_b32_dpp v89, v100 row_shr:1 row_mask:0xf bank_mask:0xf
	v_fma_f32 v121, v81, v121, v112
	v_mov_b32_dpp v119, v100 row_shr:2 row_mask:0xf bank_mask:0xf
	v_fma_f32 v112, v88, v100, v84
	v_fmac_f32_e32 v112, v92, v89
	v_fma_f32 v89, v80, v119, v112
	v_mul_f32_e32 v111, v121, v121
	v_fmamk_f32 v111, v111, 0xbdd2d3e8, v206
	v_mul_f32_e32 v112, v89, v89
	v_mul_f32_e32 v111, v121, v111
	v_fmamk_f32 v112, v112, 0xbdd2d3e8, v206
	v_exp_f32_e32 v111, v111
	v_mul_f32_e32 v112, v89, v112
	v_exp_f32_e32 v112, v112
	v_mul_f32_e32 v91, v110, v91
	v_add_f32_e32 v110, 1.0, v111
	v_rcp_f32_e32 v113, v110
	v_add_f32_e32 v110, 1.0, v112
	v_mov_b32_dpp v185, v107 row_shr:1 row_mask:0xf bank_mask:0xf
	v_rcp_f32_e32 v112, v110
	v_mov_b32_dpp v118, v107 row_shr:2 row_mask:0xf bank_mask:0xf
	v_fma_f32 v110, v184, v107, v71
	v_fmac_f32_e32 v110, v79, v185
	v_mov_b32_dpp v75, v106 row_shr:1 row_mask:0xf bank_mask:0xf
	v_fma_f32 v118, v67, v118, v110
	v_mul_f32_e32 v110, v118, v118
	v_fmamk_f32 v110, v110, 0xbdd2d3e8, v206
	v_mul_f32_e32 v110, v118, v110
	v_exp_f32_e32 v110, v110
	v_mul_f32_e32 v111, v121, v113
	v_mul_f32_e32 v113, v109, v111
	v_add_f32_e32 v109, 1.0, v110
	v_mov_b32_dpp v117, v106 row_shr:2 row_mask:0xf bank_mask:0xf
	v_fma_f32 v110, v74, v106, v70
	v_fmac_f32_e32 v110, v78, v75
	v_rcp_f32_e32 v109, v109
	v_fma_f32 v75, v66, v117, v110
	v_mul_f32_e32 v110, v75, v75
	v_fmamk_f32 v110, v110, 0xbdd2d3e8, v206
	v_mul_f32_e32 v110, v75, v110
	v_exp_f32_e32 v110, v110
	v_mul_f32_e32 v89, v89, v112
	v_mul_f32_e32 v89, v108, v89
	v_mul_f32_e32 v108, v118, v109
	v_mul_f32_e32 v99, v99, v108
	v_add_f32_e32 v108, 1.0, v110
	v_mov_b32_dpp v183, v105 row_shr:1 row_mask:0xf bank_mask:0xf
	v_rcp_f32_e32 v110, v108
	v_mov_b32_dpp v116, v105 row_shr:2 row_mask:0xf bank_mask:0xf
	v_fma_f32 v108, v182, v105, v69
	v_fmac_f32_e32 v108, v77, v183
	v_mov_b32_dpp v73, v104 row_shr:1 row_mask:0xf bank_mask:0xf
	v_fma_f32 v111, v65, v116, v108
	v_mul_f32_e32 v108, v111, v111
	v_fmamk_f32 v108, v108, 0xbdd2d3e8, v206
	v_mul_f32_e32 v108, v111, v108
	v_exp_f32_e32 v112, v108
	v_mov_b32_dpp v120, v104 row_shr:2 row_mask:0xf bank_mask:0xf
	v_fma_f32 v108, v72, v104, v68
	v_fmac_f32_e32 v108, v76, v73
	v_or_b32_e32 v115, 48, v208
	v_fma_f32 v73, v64, v120, v108
	v_mul_f32_e32 v108, v73, v73
	v_fmamk_f32 v108, v108, 0xbdd2d3e8, v206
	v_mul_f32_e32 v108, v73, v108
	v_exp_f32_e32 v108, v108
	v_add_f32_e32 v109, 1.0, v112
	v_rcp_f32_e32 v109, v109
	v_mul_f32_e32 v75, v75, v110
	v_add_f32_e32 v108, 1.0, v108
	v_rcp_f32_e32 v108, v108
	v_mul_f32_e32 v75, v98, v75
	v_mul_f32_e32 v98, v111, v109
	v_mul_f32_e32 v97, v97, v98
	v_mul_f32_e32 v73, v73, v108
	v_mad_i64_i32 v[108:109], s[0:1], v115, s83, v[138:139]
	v_lshl_add_u64 v[108:109], v[108:109], 0, v[136:137]
	v_mul_f32_e32 v73, v96, v73
	v_cvt_pk_bf16_f32 v96, v73, v97
	v_cvt_pk_bf16_f32 v97, v75, v99
	v_cvt_pk_bf16_f32 v98, v89, v113
	v_cvt_pk_bf16_f32 v99, v91, v114
	global_store_dwordx4 v[108:109], v[96:99], off
	s_and_saveexec_b64 s[64:65], s[4:5]
	s_cbranch_execz .LBB0_1561
	v_lshl_add_u64 v[96:97], s[62:63], 0, v[170:171]
	v_mov_b64_e32 v[98:99], s[18:19]
	v_mad_u64_u32 v[98:99], s[0:1], v96, s82, v[98:99]
	v_mad_i32_i24 v99, v97, s82, v99
	v_lshl_add_u64 v[96:97], v[180:181], 2, v[98:99]
	global_store_dwordx4 v[96:97], v[104:107], off
	global_store_dwordx4 v[96:97], v[100:103], off offset:16
.LBB0_1561:
	s_or_b64 exec, exec, s[64:65]
	s_add_i32 s0, s60, 2
	s_ashr_i32 s1, s0, 31
	v_mov_b32_dpp v73, v52 row_ror:1 row_mask:0xf bank_mask:0xf
	v_mov_b32_dpp v96, v52 row_ror:2 row_mask:0xf bank_mask:0xf
	v_mov_b32_dpp v183, v53 row_ror:1 row_mask:0xf bank_mask:0xf
	v_mov_b32_dpp v97, v53 row_ror:2 row_mask:0xf bank_mask:0xf
	v_mov_b32_dpp v75, v54 row_ror:1 row_mask:0xf bank_mask:0xf
	v_mov_b32_dpp v98, v54 row_ror:2 row_mask:0xf bank_mask:0xf
	v_mov_b32_dpp v185, v55 row_ror:1 row_mask:0xf bank_mask:0xf
	v_mov_b32_dpp v99, v55 row_ror:2 row_mask:0xf bank_mask:0xf
	v_mov_b32_dpp v89, v48 row_ror:1 row_mask:0xf bank_mask:0xf
	v_mov_b32_dpp v100, v48 row_ror:2 row_mask:0xf bank_mask:0xf
	v_mov_b32_dpp v187, v49 row_ror:1 row_mask:0xf bank_mask:0xf
	v_mov_b32_dpp v101, v49 row_ror:2 row_mask:0xf bank_mask:0xf
	v_mov_b32_dpp v91, v50 row_ror:1 row_mask:0xf bank_mask:0xf
	v_mov_b32_dpp v102, v50 row_ror:2 row_mask:0xf bank_mask:0xf
	v_mov_b32_dpp v189, v51 row_ror:1 row_mask:0xf bank_mask:0xf
	v_mov_b32_dpp v103, v51 row_ror:2 row_mask:0xf bank_mask:0xf
	s_lshl_b64 s[60:61], s[0:1], 1
	v_mov_b32_dpp v73, v52 row_shr:1 row_mask:0xf bank_mask:0xf
	v_mov_b32_dpp v96, v52 row_shr:2 row_mask:0xf bank_mask:0xf
	v_mov_b32_dpp v183, v53 row_shr:1 row_mask:0xf bank_mask:0xf
	v_mov_b32_dpp v97, v53 row_shr:2 row_mask:0xf bank_mask:0xf
	v_mov_b32_dpp v75, v54 row_shr:1 row_mask:0xf bank_mask:0xf
	v_mov_b32_dpp v98, v54 row_shr:2 row_mask:0xf bank_mask:0xf
	v_mov_b32_dpp v185, v55 row_shr:1 row_mask:0xf bank_mask:0xf
	v_mov_b32_dpp v99, v55 row_shr:2 row_mask:0xf bank_mask:0xf
	v_mov_b32_dpp v89, v48 row_shr:1 row_mask:0xf bank_mask:0xf
	v_mov_b32_dpp v100, v48 row_shr:2 row_mask:0xf bank_mask:0xf
	v_mov_b32_dpp v187, v49 row_shr:1 row_mask:0xf bank_mask:0xf
	v_mov_b32_dpp v101, v49 row_shr:2 row_mask:0xf bank_mask:0xf
	v_mov_b32_dpp v91, v50 row_shr:1 row_mask:0xf bank_mask:0xf
	v_mov_b32_dpp v102, v50 row_shr:2 row_mask:0xf bank_mask:0xf
	v_mov_b32_dpp v189, v51 row_shr:1 row_mask:0xf bank_mask:0xf
	v_mov_b32_dpp v103, v51 row_shr:2 row_mask:0xf bank_mask:0xf
	s_and_saveexec_b64 s[0:1], s[2:3]
	s_xor_b64 s[62:63], exec, s[0:1]
	s_cbranch_execz .LBB0_1563
	v_or_b32_e32 v73, s60, v168
	v_mov_b64_e32 v[96:97], s[20:21]
	v_mov_b64_e32 v[98:99], s[34:35]
	v_mad_u64_u32 v[96:97], s[0:1], v73, s82, v[96:97]
	v_mad_u64_u32 v[98:99], s[0:1], v73, s82, v[98:99]
	v_mad_i32_i24 v97, s61, v207, v97
	v_mad_i32_i24 v99, s61, v207, v99
	v_lshl_add_u64 v[96:97], v[96:97], 0, v[190:191]
	v_lshl_add_u64 v[98:99], v[98:99], 0, v[190:191]
	global_store_dwordx4 v[96:97], v[52:55], off
	global_store_dwordx4 v[96:97], v[48:51], off offset:16
	global_store_dwordx4 v[98:99], v[56:59], off
	global_store_dwordx4 v[98:99], v[60:63], off offset:16
.LBB0_1563:
	s_andn2_saveexec_b64 s[62:63], s[62:63]
	s_cbranch_execz .LBB0_1565
	v_fma_f32 v104, v188, v51, v87
	v_fmac_f32_e32 v104, v95, v189
	s_nop 0
	v_fma_f32 v103, v83, v103, v104
	v_mul_f32_e32 v104, v103, v103
	v_fmamk_f32 v104, v104, 0xbdd2d3e8, v206
	v_mul_f32_e32 v104, v103, v104
	v_exp_f32_e32 v106, v104
	v_fma_f32 v104, v90, v50, v86
	v_fmac_f32_e32 v104, v94, v91
	s_nop 0
	v_fma_f32 v91, v82, v102, v104
	v_mul_f32_e32 v102, v91, v91
	v_fmamk_f32 v102, v102, 0xbdd2d3e8, v206
	v_mul_f32_e32 v102, v91, v102
	v_exp_f32_e32 v102, v102
	v_add_f32_e32 v104, 1.0, v106
	v_rcp_f32_e32 v104, v104
	v_add_f32_e32 v102, 1.0, v102
	v_rcp_f32_e32 v102, v102
	v_mul_f32_e32 v103, v103, v104
	v_mul_f32_e32 v104, v63, v103
	v_mul_f32_e32 v63, v91, v102
	v_fma_f32 v102, v186, v49, v85
	v_fmac_f32_e32 v102, v93, v187
	s_nop 0
	v_fma_f32 v91, v81, v101, v102
	v_fma_f32 v102, v88, v48, v84
	v_fmac_f32_e32 v102, v92, v89
	v_fma_f32 v89, v80, v100, v102
	v_mul_f32_e32 v101, v91, v91
	v_fmamk_f32 v101, v101, 0xbdd2d3e8, v206
	v_mul_f32_e32 v100, v89, v89
	v_mul_f32_e32 v101, v91, v101
	v_fmamk_f32 v100, v100, 0xbdd2d3e8, v206
	v_exp_f32_e32 v101, v101
	v_mul_f32_e32 v100, v89, v100
	v_exp_f32_e32 v100, v100
	v_mul_f32_e32 v102, v62, v63
	v_add_f32_e32 v62, 1.0, v101
	v_rcp_f32_e32 v101, v62
	v_add_f32_e32 v62, 1.0, v100
	v_rcp_f32_e32 v100, v62
	v_fma_f32 v62, v184, v55, v71
	v_fmac_f32_e32 v62, v79, v185
	s_nop 0
	v_fma_f32 v99, v67, v99, v62
	v_mul_f32_e32 v62, v99, v99
	v_fmamk_f32 v62, v62, 0xbdd2d3e8, v206
	v_mul_f32_e32 v62, v99, v62
	v_exp_f32_e32 v62, v62
	v_mul_f32_e32 v63, v91, v101
	v_mul_f32_e32 v91, v61, v63
	v_mul_f32_e32 v61, v89, v100
	v_add_f32_e32 v62, 1.0, v62
	v_rcp_f32_e32 v89, v62
	v_fma_f32 v62, v74, v54, v70
	v_fmac_f32_e32 v62, v78, v75
	v_mul_f32_e32 v75, v60, v61
	v_fma_f32 v62, v66, v98, v62
	v_mul_f32_e32 v63, v62, v62
	v_fmamk_f32 v63, v63, 0xbdd2d3e8, v206
	v_mul_f32_e32 v63, v62, v63
	v_exp_f32_e32 v63, v63
	v_mul_f32_e32 v60, v99, v89
	v_mul_f32_e32 v59, v59, v60
	v_add_f32_e32 v60, 1.0, v63
	v_rcp_f32_e32 v63, v60
	v_fma_f32 v60, v182, v53, v69
	v_fmac_f32_e32 v60, v77, v183
	v_mul_f32_e32 v62, v62, v63
	v_fma_f32 v89, v65, v97, v60
	v_mul_f32_e32 v60, v89, v89
	v_fmamk_f32 v60, v60, 0xbdd2d3e8, v206
	v_mul_f32_e32 v60, v89, v60
	v_exp_f32_e32 v97, v60
	v_fma_f32 v60, v72, v52, v68
	v_fmac_f32_e32 v60, v76, v73
	v_add_f32_e32 v63, 1.0, v97
	v_fma_f32 v60, v64, v96, v60
	v_mul_f32_e32 v61, v60, v60
	v_fmamk_f32 v61, v61, 0xbdd2d3e8, v206
	v_mul_f32_e32 v61, v60, v61
	v_exp_f32_e32 v61, v61
	v_rcp_f32_e32 v63, v63
	v_mul_f32_e32 v58, v58, v62
	v_add_f32_e32 v61, 1.0, v61
	v_rcp_f32_e32 v61, v61
	v_mul_f32_e32 v62, v89, v63
	v_mul_f32_e32 v57, v57, v62
	v_add_u32_e32 v62, 0x80, v208
	v_mul_f32_e32 v60, v60, v61
	v_mul_f32_e32 v56, v56, v60
	v_mov_b64_e32 v[60:61], s[10:11]
	v_mad_i64_i32 v[60:61], s[0:1], v62, s83, v[60:61]
	v_lshl_add_u64 v[60:61], v[180:181], 1, v[60:61]
	v_cvt_pk_bf16_f32 v56, v56, v57
	v_cvt_pk_bf16_f32 v57, v58, v59
	v_cvt_pk_bf16_f32 v58, v75, v91
	v_cvt_pk_bf16_f32 v59, v102, v104
	global_store_dwordx4 v[60:61], v[56:59], off
.LBB0_1565:
	s_or_b64 exec, exec, s[62:63]
	v_mov_b32_dpp v73, v52 row_ror:1 row_mask:0xf bank_mask:0xf
	v_mov_b32_dpp v56, v52 row_ror:2 row_mask:0xf bank_mask:0xf
	v_mov_b32_dpp v183, v53 row_ror:1 row_mask:0xf bank_mask:0xf
	v_mov_b32_dpp v52, v53 row_ror:2 row_mask:0xf bank_mask:0xf
	v_mov_b32_dpp v75, v54 row_ror:1 row_mask:0xf bank_mask:0xf
	v_mov_b32_dpp v53, v54 row_ror:2 row_mask:0xf bank_mask:0xf
	v_mov_b32_dpp v185, v55 row_ror:1 row_mask:0xf bank_mask:0xf
	v_mov_b32_dpp v54, v55 row_ror:2 row_mask:0xf bank_mask:0xf
	v_mov_b32_dpp v91, v50 row_ror:1 row_mask:0xf bank_mask:0xf
	v_mov_b32_dpp v58, v50 row_ror:2 row_mask:0xf bank_mask:0xf
	v_mov_b32_dpp v189, v51 row_ror:1 row_mask:0xf bank_mask:0xf
	v_mov_b32_dpp v89, v48 row_ror:1 row_mask:0xf bank_mask:0xf
	v_mov_b32_dpp v55, v48 row_ror:2 row_mask:0xf bank_mask:0xf
	v_mov_b32_dpp v187, v49 row_ror:1 row_mask:0xf bank_mask:0xf
	v_mov_b32_dpp v57, v49 row_ror:2 row_mask:0xf bank_mask:0xf
	v_mov_b32_dpp v189, v35 row_shr:1 row_mask:0xf bank_mask:0xf
	v_mov_b32_dpp v50, v51 row_ror:2 row_mask:0xf bank_mask:0xf
	v_mov_b32_dpp v50, v35 row_shr:2 row_mask:0xf bank_mask:0xf
	v_fma_f32 v48, v188, v35, v87
	v_fmac_f32_e32 v48, v95, v189
	v_mov_b32_dpp v91, v34 row_shr:1 row_mask:0xf bank_mask:0xf
	v_fma_f32 v50, v83, v50, v48
	v_mul_f32_e32 v48, v50, v50
	v_fmamk_f32 v48, v48, 0xbdd2d3e8, v206
	v_mul_f32_e32 v48, v50, v48
	v_exp_f32_e32 v51, v48
	v_mov_b32_dpp v58, v34 row_shr:2 row_mask:0xf bank_mask:0xf
	v_fma_f32 v48, v90, v34, v86
	v_fmac_f32_e32 v48, v94, v91
	v_add_f32_e32 v51, 1.0, v51
	v_fma_f32 v48, v82, v58, v48
	v_mul_f32_e32 v49, v48, v48
	v_fmamk_f32 v49, v49, 0xbdd2d3e8, v206
	v_mul_f32_e32 v49, v48, v49
	v_exp_f32_e32 v49, v49
	v_rcp_f32_e32 v51, v51
	v_mov_b32_dpp v187, v33 row_shr:1 row_mask:0xf bank_mask:0xf
	v_mov_b32_dpp v57, v33 row_shr:2 row_mask:0xf bank_mask:0xf
	v_add_f32_e32 v49, 1.0, v49
	v_rcp_f32_e32 v49, v49
	v_mul_f32_e32 v50, v50, v51
	v_mul_f32_e32 v50, v47, v50
	v_mov_b32_dpp v89, v32 row_shr:1 row_mask:0xf bank_mask:0xf
	v_mul_f32_e32 v47, v48, v49
	v_fma_f32 v48, v186, v33, v85
	v_fmac_f32_e32 v48, v93, v187
	v_mov_b32_dpp v55, v32 row_shr:2 row_mask:0xf bank_mask:0xf
	v_fma_f32 v51, v81, v57, v48
	v_mul_f32_e32 v48, v51, v51
	v_fmamk_f32 v48, v48, 0xbdd2d3e8, v206
	v_mul_f32_e32 v48, v51, v48
	v_exp_f32_e32 v57, v48
	v_fma_f32 v48, v88, v32, v84
	v_fmac_f32_e32 v48, v92, v89
	v_mov_b32_dpp v185, v39 row_shr:1 row_mask:0xf bank_mask:0xf
	v_fma_f32 v48, v80, v55, v48
	v_mul_f32_e32 v49, v48, v48
	v_fmamk_f32 v49, v49, 0xbdd2d3e8, v206
	v_mul_f32_e32 v49, v48, v49
	v_exp_f32_e32 v49, v49
	v_mul_f32_e32 v55, v46, v47
	v_add_f32_e32 v46, 1.0, v57
	v_rcp_f32_e32 v57, v46
	v_add_f32_e32 v46, 1.0, v49
	v_rcp_f32_e32 v49, v46
	v_mov_b32_dpp v54, v39 row_shr:2 row_mask:0xf bank_mask:0xf
	v_fma_f32 v46, v184, v39, v71
	v_fmac_f32_e32 v46, v79, v185
	v_mov_b32_dpp v75, v38 row_shr:1 row_mask:0xf bank_mask:0xf
	v_fma_f32 v54, v67, v54, v46
	v_mul_f32_e32 v46, v54, v54
	v_fmamk_f32 v46, v46, 0xbdd2d3e8, v206
	v_mul_f32_e32 v46, v54, v46
	v_exp_f32_e32 v46, v46
	v_mul_f32_e32 v47, v51, v57
	v_mul_f32_e32 v51, v45, v47
	v_mul_f32_e32 v45, v48, v49
	v_add_f32_e32 v46, 1.0, v46
	v_rcp_f32_e32 v48, v46
	v_mov_b32_dpp v53, v38 row_shr:2 row_mask:0xf bank_mask:0xf
	v_fma_f32 v46, v74, v38, v70
	v_fmac_f32_e32 v46, v78, v75
	v_mul_f32_e32 v49, v44, v45
	v_fma_f32 v46, v66, v53, v46
	v_mul_f32_e32 v47, v46, v46
	v_fmamk_f32 v47, v47, 0xbdd2d3e8, v206
	v_mul_f32_e32 v47, v46, v47
	v_exp_f32_e32 v47, v47
	v_mul_f32_e32 v44, v54, v48
	v_mul_f32_e32 v43, v43, v44
	v_mov_b32_dpp v183, v37 row_shr:1 row_mask:0xf bank_mask:0xf
	v_add_f32_e32 v44, 1.0, v47
	v_rcp_f32_e32 v47, v44
	v_mov_b32_dpp v52, v37 row_shr:2 row_mask:0xf bank_mask:0xf
	v_fma_f32 v44, v182, v37, v69
	v_fmac_f32_e32 v44, v77, v183
	v_mov_b32_dpp v73, v36 row_shr:1 row_mask:0xf bank_mask:0xf
	v_fma_f32 v48, v65, v52, v44
	v_mul_f32_e32 v44, v48, v48
	v_fmamk_f32 v44, v44, 0xbdd2d3e8, v206
	v_mul_f32_e32 v44, v48, v44
	v_exp_f32_e32 v52, v44
	v_mov_b32_dpp v56, v36 row_shr:2 row_mask:0xf bank_mask:0xf
	v_fma_f32 v44, v72, v36, v68
	v_fmac_f32_e32 v44, v76, v73
	v_mul_f32_e32 v46, v46, v47
	v_fma_f32 v44, v64, v56, v44
	v_mul_f32_e32 v45, v44, v44
	v_fmamk_f32 v45, v45, 0xbdd2d3e8, v206
	v_mul_f32_e32 v45, v44, v45
	v_exp_f32_e32 v45, v45
	v_add_f32_e32 v47, 1.0, v52
	v_rcp_f32_e32 v47, v47
	v_mul_f32_e32 v46, v42, v46
	v_add_f32_e32 v45, 1.0, v45
	v_rcp_f32_e32 v45, v45
	v_mul_f32_e32 v42, v48, v47
	v_mul_f32_e32 v41, v41, v42
	v_add_u32_e32 v58, 0x90, v208
	v_mul_f32_e32 v42, v44, v45
	v_mul_f32_e32 v40, v40, v42
	v_cvt_pk_bf16_f32 v42, v40, v41
	v_mov_b64_e32 v[40:41], s[10:11]
	v_cvt_pk_bf16_f32 v43, v46, v43
	v_mad_i64_i32 v[46:47], s[0:1], v58, s83, v[40:41]
	v_lshl_add_u64 v[46:47], v[46:47], 0, v[136:137]
	v_cvt_pk_bf16_f32 v44, v49, v51
	v_cvt_pk_bf16_f32 v45, v55, v50
	global_store_dwordx4 v[46:47], v[42:45], off
	v_mov_b32_dpp v73, v36 row_ror:1 row_mask:0xf bank_mask:0xf
	v_mov_b32_dpp v183, v37 row_ror:1 row_mask:0xf bank_mask:0xf
	v_mov_b32_dpp v42, v36 row_ror:2 row_mask:0xf bank_mask:0xf
	v_mov_b32_dpp v36, v37 row_ror:2 row_mask:0xf bank_mask:0xf
	v_mov_b32_dpp v75, v38 row_ror:1 row_mask:0xf bank_mask:0xf
	v_mov_b32_dpp v37, v38 row_ror:2 row_mask:0xf bank_mask:0xf
	v_mov_b32_dpp v185, v39 row_ror:1 row_mask:0xf bank_mask:0xf
	v_mov_b32_dpp v38, v39 row_ror:2 row_mask:0xf bank_mask:0xf
	v_mov_b32_dpp v91, v34 row_ror:1 row_mask:0xf bank_mask:0xf
	v_mov_b32_dpp v44, v34 row_ror:2 row_mask:0xf bank_mask:0xf
	v_mov_b32_dpp v189, v35 row_ror:1 row_mask:0xf bank_mask:0xf
	v_mov_b32_dpp v89, v32 row_ror:1 row_mask:0xf bank_mask:0xf
	v_mov_b32_dpp v39, v32 row_ror:2 row_mask:0xf bank_mask:0xf
	v_mov_b32_dpp v187, v33 row_ror:1 row_mask:0xf bank_mask:0xf
	v_mov_b32_dpp v43, v33 row_ror:2 row_mask:0xf bank_mask:0xf
	v_mov_b32_dpp v189, v19 row_shr:1 row_mask:0xf bank_mask:0xf
	v_mov_b32_dpp v34, v35 row_ror:2 row_mask:0xf bank_mask:0xf
	v_mov_b32_dpp v34, v19 row_shr:2 row_mask:0xf bank_mask:0xf
	v_fma_f32 v32, v188, v19, v87
	v_fmac_f32_e32 v32, v95, v189
	v_mov_b32_dpp v91, v18 row_shr:1 row_mask:0xf bank_mask:0xf
	v_fma_f32 v34, v83, v34, v32
	v_mul_f32_e32 v32, v34, v34
	v_fmamk_f32 v32, v32, 0xbdd2d3e8, v206
	v_mul_f32_e32 v32, v34, v32
	v_exp_f32_e32 v35, v32
	v_mov_b32_dpp v44, v18 row_shr:2 row_mask:0xf bank_mask:0xf
	v_fma_f32 v32, v90, v18, v86
	v_fmac_f32_e32 v32, v94, v91
	v_add_f32_e32 v35, 1.0, v35
	v_fma_f32 v32, v82, v44, v32
	v_mul_f32_e32 v33, v32, v32
	v_fmamk_f32 v33, v33, 0xbdd2d3e8, v206
	v_mul_f32_e32 v33, v32, v33
	v_exp_f32_e32 v33, v33
	v_rcp_f32_e32 v35, v35
	v_mov_b32_dpp v187, v17 row_shr:1 row_mask:0xf bank_mask:0xf
	v_mov_b32_dpp v43, v17 row_shr:2 row_mask:0xf bank_mask:0xf
	v_add_f32_e32 v33, 1.0, v33
	v_rcp_f32_e32 v33, v33
	v_mul_f32_e32 v34, v34, v35
	v_mul_f32_e32 v34, v31, v34
	v_mov_b32_dpp v89, v16 row_shr:1 row_mask:0xf bank_mask:0xf
	v_mul_f32_e32 v31, v32, v33
	v_fma_f32 v32, v186, v17, v85
	v_fmac_f32_e32 v32, v93, v187
	v_mov_b32_dpp v39, v16 row_shr:2 row_mask:0xf bank_mask:0xf
	v_fma_f32 v35, v81, v43, v32
	v_mul_f32_e32 v32, v35, v35
	v_fmamk_f32 v32, v32, 0xbdd2d3e8, v206
	v_mul_f32_e32 v32, v35, v32
	v_exp_f32_e32 v43, v32
	v_fma_f32 v32, v88, v16, v84
	v_fmac_f32_e32 v32, v92, v89
	v_mov_b32_dpp v185, v23 row_shr:1 row_mask:0xf bank_mask:0xf
	v_fma_f32 v32, v80, v39, v32
	v_mul_f32_e32 v33, v32, v32
	v_fmamk_f32 v33, v33, 0xbdd2d3e8, v206
	v_mul_f32_e32 v33, v32, v33
	v_exp_f32_e32 v33, v33
	v_mul_f32_e32 v39, v30, v31
	v_add_f32_e32 v30, 1.0, v43
	v_rcp_f32_e32 v43, v30
	v_add_f32_e32 v30, 1.0, v33
	v_rcp_f32_e32 v33, v30
	v_mov_b32_dpp v38, v23 row_shr:2 row_mask:0xf bank_mask:0xf
	v_fma_f32 v30, v184, v23, v71
	v_fmac_f32_e32 v30, v79, v185
	v_mov_b32_dpp v75, v22 row_shr:1 row_mask:0xf bank_mask:0xf
	v_fma_f32 v38, v67, v38, v30
	v_mul_f32_e32 v30, v38, v38
	v_fmamk_f32 v30, v30, 0xbdd2d3e8, v206
	v_mul_f32_e32 v30, v38, v30
	v_exp_f32_e32 v30, v30
	v_mul_f32_e32 v31, v35, v43
	v_mul_f32_e32 v35, v29, v31
	v_mul_f32_e32 v29, v32, v33
	v_add_f32_e32 v30, 1.0, v30
	v_rcp_f32_e32 v32, v30
	v_mov_b32_dpp v37, v22 row_shr:2 row_mask:0xf bank_mask:0xf
	v_fma_f32 v30, v74, v22, v70
	v_fmac_f32_e32 v30, v78, v75
	v_mul_f32_e32 v33, v28, v29
	v_fma_f32 v30, v66, v37, v30
	v_mul_f32_e32 v31, v30, v30
	v_fmamk_f32 v31, v31, 0xbdd2d3e8, v206
	v_mul_f32_e32 v31, v30, v31
	v_exp_f32_e32 v31, v31
	v_mul_f32_e32 v28, v38, v32
	v_mul_f32_e32 v27, v27, v28
	v_mov_b32_dpp v183, v21 row_shr:1 row_mask:0xf bank_mask:0xf
	v_add_f32_e32 v28, 1.0, v31
	v_rcp_f32_e32 v31, v28
	v_mov_b32_dpp v36, v21 row_shr:2 row_mask:0xf bank_mask:0xf
	v_fma_f32 v28, v182, v21, v69
	v_fmac_f32_e32 v28, v77, v183
	v_mov_b32_dpp v73, v20 row_shr:1 row_mask:0xf bank_mask:0xf
	v_fma_f32 v32, v65, v36, v28
	v_mul_f32_e32 v28, v32, v32
	v_fmamk_f32 v28, v28, 0xbdd2d3e8, v206
	v_mul_f32_e32 v28, v32, v28
	v_exp_f32_e32 v36, v28
	v_mov_b32_dpp v42, v20 row_shr:2 row_mask:0xf bank_mask:0xf
	v_fma_f32 v28, v72, v20, v68
	v_fmac_f32_e32 v28, v76, v73
	v_mul_f32_e32 v30, v30, v31
	v_fma_f32 v28, v64, v42, v28
	v_mul_f32_e32 v29, v28, v28
	v_fmamk_f32 v29, v29, 0xbdd2d3e8, v206
	v_mul_f32_e32 v29, v28, v29
	v_exp_f32_e32 v29, v29
	v_add_f32_e32 v31, 1.0, v36
	v_rcp_f32_e32 v31, v31
	v_add_u32_e32 v44, 0xa0, v208
	v_add_f32_e32 v29, 1.0, v29
	v_rcp_f32_e32 v29, v29
	v_mul_f32_e32 v26, v26, v30
	v_mul_f32_e32 v30, v32, v31
	v_mul_f32_e32 v25, v25, v30
	v_mul_f32_e32 v28, v28, v29
	v_mul_f32_e32 v24, v24, v28
	v_mad_i64_i32 v[28:29], s[0:1], v44, s83, v[40:41]
	v_cvt_pk_bf16_f32 v24, v24, v25
	v_lshl_add_u64 v[28:29], v[28:29], 0, v[136:137]
	v_cvt_pk_bf16_f32 v25, v26, v27
	v_cvt_pk_bf16_f32 v26, v33, v35
	v_cvt_pk_bf16_f32 v27, v39, v34
	global_store_dwordx4 v[28:29], v[24:27], off
	v_mov_b32_dpp v73, v20 row_ror:1 row_mask:0xf bank_mask:0xf
	v_mov_b32_dpp v183, v21 row_ror:1 row_mask:0xf bank_mask:0xf
	v_mov_b32_dpp v24, v20 row_ror:2 row_mask:0xf bank_mask:0xf
	v_mov_b32_dpp v20, v21 row_ror:2 row_mask:0xf bank_mask:0xf
	v_mov_b32_dpp v75, v22 row_ror:1 row_mask:0xf bank_mask:0xf
	v_mov_b32_dpp v21, v22 row_ror:2 row_mask:0xf bank_mask:0xf
	v_mov_b32_dpp v185, v23 row_ror:1 row_mask:0xf bank_mask:0xf
	v_mov_b32_dpp v22, v23 row_ror:2 row_mask:0xf bank_mask:0xf
	v_mov_b32_dpp v91, v18 row_ror:1 row_mask:0xf bank_mask:0xf
	v_mov_b32_dpp v26, v18 row_ror:2 row_mask:0xf bank_mask:0xf
	v_mov_b32_dpp v189, v19 row_ror:1 row_mask:0xf bank_mask:0xf
	v_mov_b32_dpp v89, v16 row_ror:1 row_mask:0xf bank_mask:0xf
	v_mov_b32_dpp v23, v16 row_ror:2 row_mask:0xf bank_mask:0xf
	v_mov_b32_dpp v187, v17 row_ror:1 row_mask:0xf bank_mask:0xf
	v_mov_b32_dpp v25, v17 row_ror:2 row_mask:0xf bank_mask:0xf
	v_mov_b32_dpp v189, v7 row_shr:1 row_mask:0xf bank_mask:0xf
	v_mov_b32_dpp v18, v19 row_ror:2 row_mask:0xf bank_mask:0xf
	v_mov_b32_dpp v18, v7 row_shr:2 row_mask:0xf bank_mask:0xf
	v_fma_f32 v16, v188, v7, v87
	v_fmac_f32_e32 v16, v95, v189
	v_mov_b32_dpp v91, v6 row_shr:1 row_mask:0xf bank_mask:0xf
	v_fma_f32 v18, v83, v18, v16
	v_mul_f32_e32 v16, v18, v18
	v_fmamk_f32 v16, v16, 0xbdd2d3e8, v206
	v_mul_f32_e32 v16, v18, v16
	v_exp_f32_e32 v19, v16
	v_mov_b32_dpp v26, v6 row_shr:2 row_mask:0xf bank_mask:0xf
	v_fma_f32 v16, v90, v6, v86
	v_fmac_f32_e32 v16, v94, v91
	v_add_f32_e32 v19, 1.0, v19
	v_fma_f32 v16, v82, v26, v16
	v_mul_f32_e32 v17, v16, v16
	v_fmamk_f32 v17, v17, 0xbdd2d3e8, v206
	v_mul_f32_e32 v17, v16, v17
	v_exp_f32_e32 v17, v17
	v_rcp_f32_e32 v19, v19
	v_mov_b32_dpp v187, v5 row_shr:1 row_mask:0xf bank_mask:0xf
	v_mov_b32_dpp v25, v5 row_shr:2 row_mask:0xf bank_mask:0xf
	v_add_f32_e32 v17, 1.0, v17
	v_rcp_f32_e32 v17, v17
	v_mul_f32_e32 v18, v18, v19
	v_mul_f32_e32 v18, v15, v18
	v_mov_b32_dpp v89, v4 row_shr:1 row_mask:0xf bank_mask:0xf
	v_mul_f32_e32 v15, v16, v17
	v_fma_f32 v16, v186, v5, v85
	v_fmac_f32_e32 v16, v93, v187
	v_mov_b32_dpp v23, v4 row_shr:2 row_mask:0xf bank_mask:0xf
	v_fma_f32 v19, v81, v25, v16
	v_mul_f32_e32 v16, v19, v19
	v_fmamk_f32 v16, v16, 0xbdd2d3e8, v206
	v_mul_f32_e32 v16, v19, v16
	v_exp_f32_e32 v25, v16
	v_fma_f32 v16, v88, v4, v84
	v_fmac_f32_e32 v16, v92, v89
	v_mov_b32_dpp v185, v11 row_shr:1 row_mask:0xf bank_mask:0xf
	v_fma_f32 v16, v80, v23, v16
	v_mul_f32_e32 v17, v16, v16
	v_fmamk_f32 v17, v17, 0xbdd2d3e8, v206
	v_mul_f32_e32 v17, v16, v17
	v_exp_f32_e32 v17, v17
	v_mul_f32_e32 v23, v14, v15
	v_add_f32_e32 v14, 1.0, v25
	v_rcp_f32_e32 v25, v14
	v_add_f32_e32 v14, 1.0, v17
	v_rcp_f32_e32 v17, v14
	v_mov_b32_dpp v22, v11 row_shr:2 row_mask:0xf bank_mask:0xf
	v_fma_f32 v14, v184, v11, v71
	v_fmac_f32_e32 v14, v79, v185
	v_mov_b32_dpp v75, v10 row_shr:1 row_mask:0xf bank_mask:0xf
	v_fma_f32 v22, v67, v22, v14
	v_mul_f32_e32 v14, v22, v22
	v_fmamk_f32 v14, v14, 0xbdd2d3e8, v206
	v_mul_f32_e32 v14, v22, v14
	v_exp_f32_e32 v14, v14
	v_mul_f32_e32 v15, v19, v25
	v_mul_f32_e32 v19, v13, v15
	v_mul_f32_e32 v13, v16, v17
	v_add_f32_e32 v14, 1.0, v14
	v_rcp_f32_e32 v16, v14
	v_mov_b32_dpp v21, v10 row_shr:2 row_mask:0xf bank_mask:0xf
	v_fma_f32 v14, v74, v10, v70
	v_fmac_f32_e32 v14, v78, v75
	v_mul_f32_e32 v17, v12, v13
	v_fma_f32 v14, v66, v21, v14
	v_mul_f32_e32 v15, v14, v14
	v_fmamk_f32 v15, v15, 0xbdd2d3e8, v206
	v_mul_f32_e32 v15, v14, v15
	v_exp_f32_e32 v15, v15
	v_mul_f32_e32 v12, v22, v16
	v_mul_f32_e32 v3, v3, v12
	v_mov_b32_dpp v183, v9 row_shr:1 row_mask:0xf bank_mask:0xf
	v_add_f32_e32 v12, 1.0, v15
	v_rcp_f32_e32 v15, v12
	v_mov_b32_dpp v20, v9 row_shr:2 row_mask:0xf bank_mask:0xf
	v_fma_f32 v12, v182, v9, v69
	v_fmac_f32_e32 v12, v77, v183
	v_mov_b32_dpp v73, v8 row_shr:1 row_mask:0xf bank_mask:0xf
	v_fma_f32 v16, v65, v20, v12
	v_mul_f32_e32 v12, v16, v16
	v_fmamk_f32 v12, v12, 0xbdd2d3e8, v206
	v_mul_f32_e32 v12, v16, v12
	v_exp_f32_e32 v20, v12
	v_mov_b32_dpp v24, v8 row_shr:2 row_mask:0xf bank_mask:0xf
	v_fma_f32 v12, v72, v8, v68
	v_fmac_f32_e32 v12, v76, v73
	v_mul_f32_e32 v14, v14, v15
	v_fma_f32 v12, v64, v24, v12
	v_mul_f32_e32 v13, v12, v12
	v_fmamk_f32 v13, v13, 0xbdd2d3e8, v206
	v_mul_f32_e32 v13, v12, v13
	v_exp_f32_e32 v13, v13
	v_add_f32_e32 v15, 1.0, v20
	v_rcp_f32_e32 v15, v15
	v_add_u32_e32 v26, 0xb0, v208
	v_add_f32_e32 v13, 1.0, v13
	v_rcp_f32_e32 v13, v13
	v_mul_f32_e32 v2, v2, v14
	v_mul_f32_e32 v14, v16, v15
	v_mul_f32_e32 v1, v1, v14
	v_mul_f32_e32 v12, v12, v13
	v_mul_f32_e32 v0, v0, v12
	v_mad_i64_i32 v[12:13], s[0:1], v26, s83, v[40:41]
	v_lshl_add_u64 v[12:13], v[12:13], 0, v[136:137]
	v_cvt_pk_bf16_f32 v0, v0, v1
	v_cvt_pk_bf16_f32 v1, v2, v3
	v_cvt_pk_bf16_f32 v2, v17, v19
	v_cvt_pk_bf16_f32 v3, v23, v18
	global_store_dwordx4 v[12:13], v[0:3], off
	s_and_saveexec_b64 s[62:63], s[4:5]
	s_cbranch_execz .LBB0_1567
	v_lshl_add_u64 v[0:1], s[60:61], 0, v[170:171]
	v_mov_b64_e32 v[2:3], s[18:19]
	v_mad_u64_u32 v[2:3], s[0:1], v0, s82, v[2:3]
	v_mad_i32_i24 v3, v1, s82, v3
	v_lshl_add_u64 v[0:1], v[180:181], 2, v[2:3]
	global_store_dwordx4 v[0:1], v[8:11], off
	global_store_dwordx4 v[0:1], v[4:7], off offset:16
